# DSA select: register-resident exact top-256 by bitwise bisection (row loaded once, no LDS atomics, direct bitmask emission) on top of packed scan body
# speedup vs baseline: 1.0741x; 1.0199x over previous
.LBB0_961:
	s_andn2_b64 vcc, exec, s[20:21]
	s_cbranch_vccnz .LBB0_955
	s_lshl_b64 s[20:21], s[96:97], 15
	s_add_u32 s26, s90, s20
	s_addc_u32 s27, s91, s21
	s_add_u32 s26, s26, 0x62d00000
	s_addc_u32 s27, s27, 0
	s_lshl_b64 s[20:21], s[96:97], 10
	s_add_u32 s24, s94, s20
	s_addc_u32 s25, s95, s21
	s_add_i32 s22, s96, 1
	s_lshr_b32 s64, s96, 8
	s_add_i32 s63, s64, 1
	s_add_i32 s23, s63, 1
	s_and_b32 s23, s23, -2
	s_lshl_b32 s93, s64, 8
	s_sub_i32 s93, s22, s93
	v_lshlrev_b32_e32 v165, 4, v204
	v_and_b32_e32 v167, 7, v204
	v_lshlrev_b32_e32 v167, 2, v167
	v_lshrrev_b32_e32 v168, 3, v204
	v_lshlrev_b32_e32 v168, 2, v168
	v_lshlrev_b32_e32 v166, 2, v204
	v_sub_u32_e32 v169, 0x80001fff, v166
	v_sub_u32_e32 v166, s93, v166
	s_mov_b32 s80, 0x1010101
	s_mov_b32 s81, 0x1010101
	s_mov_b32 s62, 0
	global_load_dwordx4 v[32:35], v165, s[26:27] offset:0
	global_load_dwordx4 v[36:39], v165, s[26:27] offset:1024
	s_cmp_le_u32 s23, 2
	s_cbranch_scc1 .Ltk0_ld
	global_load_dwordx4 v[40:43], v165, s[26:27] offset:2048
	global_load_dwordx4 v[44:47], v165, s[26:27] offset:3072
	s_cmp_le_u32 s23, 4
	s_cbranch_scc1 .Ltk0_ld
	v_add_u32_e32 v165, 0x1000, v165
	global_load_dwordx4 v[48:51], v165, s[26:27] offset:0
	global_load_dwordx4 v[52:55], v165, s[26:27] offset:1024
	s_cmp_le_u32 s23, 6
	s_cbranch_scc1 .Ltk0_ld
	global_load_dwordx4 v[56:59], v165, s[26:27] offset:2048
	global_load_dwordx4 v[60:63], v165, s[26:27] offset:3072
	s_cmp_le_u32 s23, 8
	s_cbranch_scc1 .Ltk0_ld
	v_add_u32_e32 v165, 0x1000, v165
	global_load_dwordx4 v[64:67], v165, s[26:27] offset:0
	global_load_dwordx4 v[68:71], v165, s[26:27] offset:1024
	s_cmp_le_u32 s23, 10
	s_cbranch_scc1 .Ltk0_ld
	global_load_dwordx4 v[72:75], v165, s[26:27] offset:2048
	global_load_dwordx4 v[76:79], v165, s[26:27] offset:3072
	s_cmp_le_u32 s23, 12
	s_cbranch_scc1 .Ltk0_ld
	v_add_u32_e32 v165, 0x1000, v165
	global_load_dwordx4 v[80:83], v165, s[26:27] offset:0
	global_load_dwordx4 v[84:87], v165, s[26:27] offset:1024
	s_cmp_le_u32 s23, 14
	s_cbranch_scc1 .Ltk0_ld
	global_load_dwordx4 v[88:91], v165, s[26:27] offset:2048
	global_load_dwordx4 v[92:95], v165, s[26:27] offset:3072
	s_cmp_le_u32 s23, 16
	s_cbranch_scc1 .Ltk0_ld
	v_add_u32_e32 v165, 0x1000, v165
	global_load_dwordx4 v[96:99], v165, s[26:27] offset:0
	global_load_dwordx4 v[100:103], v165, s[26:27] offset:1024
	s_cmp_le_u32 s23, 18
	s_cbranch_scc1 .Ltk0_ld
	global_load_dwordx4 v[104:107], v165, s[26:27] offset:2048
	global_load_dwordx4 v[108:111], v165, s[26:27] offset:3072
	s_cmp_le_u32 s23, 20
	s_cbranch_scc1 .Ltk0_ld
	v_add_u32_e32 v165, 0x1000, v165
	global_load_dwordx4 v[112:115], v165, s[26:27] offset:0
	global_load_dwordx4 v[116:119], v165, s[26:27] offset:1024
	s_cmp_le_u32 s23, 22
	s_cbranch_scc1 .Ltk0_ld
	global_load_dwordx4 v[120:123], v165, s[26:27] offset:2048
	global_load_dwordx4 v[124:127], v165, s[26:27] offset:3072
	s_cmp_le_u32 s23, 24
	s_cbranch_scc1 .Ltk0_ld
	v_add_u32_e32 v165, 0x1000, v165
	global_load_dwordx4 v[128:131], v165, s[26:27] offset:0
	global_load_dwordx4 v[132:135], v165, s[26:27] offset:1024
	s_cmp_le_u32 s23, 26
	s_cbranch_scc1 .Ltk0_ld
	global_load_dwordx4 v[136:139], v165, s[26:27] offset:2048
	global_load_dwordx4 v[140:143], v165, s[26:27] offset:3072
	s_cmp_le_u32 s23, 28
	s_cbranch_scc1 .Ltk0_ld
	v_add_u32_e32 v165, 0x1000, v165
	global_load_dwordx4 v[144:147], v165, s[26:27] offset:0
	global_load_dwordx4 v[148:151], v165, s[26:27] offset:1024
	s_cmp_le_u32 s23, 30
	s_cbranch_scc1 .Ltk0_ld
	global_load_dwordx4 v[152:155], v165, s[26:27] offset:2048
	global_load_dwordx4 v[156:159], v165, s[26:27] offset:3072
.Ltk0_ld:
	s_waitcnt vmcnt(0)
	v_ashrrev_i32_e32 v162, 31, v32
	v_ashrrev_i32_e32 v163, 31, v33
	v_ashrrev_i32_e32 v164, 31, v34
	v_ashrrev_i32_e32 v170, 31, v35
	v_or_b32_e32 v162, 0x80000000, v162
	v_or_b32_e32 v163, 0x80000000, v163
	v_or_b32_e32 v164, 0x80000000, v164
	v_or_b32_e32 v170, 0x80000000, v170
	v_xor_b32_e32 v32, v32, v162
	v_xor_b32_e32 v33, v33, v163
	v_xor_b32_e32 v34, v34, v164
	v_xor_b32_e32 v35, v35, v170
	s_cmp_eq_u32 s64, 0
	s_cbranch_scc0 .Ltk0_cm0
	v_cmp_lt_i32_e64 s[34:35], 0, v166
	v_cmp_lt_i32_e64 s[36:37], 1, v166
	v_cmp_lt_i32_e64 s[48:49], 2, v166
	v_cmp_lt_i32_e64 s[50:51], 3, v166
	v_cndmask_b32_e64 v32, 0, v32, s[34:35]
	v_cndmask_b32_e64 v33, 0, v33, s[36:37]
	v_cndmask_b32_e64 v34, 0, v34, s[48:49]
	v_cndmask_b32_e64 v35, 0, v35, s[50:51]
.Ltk0_cm0:
	s_cmp_le_u32 s63, 1
	s_cbranch_scc1 .Ltk0_cz1
	v_ashrrev_i32_e32 v162, 31, v36
	v_ashrrev_i32_e32 v163, 31, v37
	v_ashrrev_i32_e32 v164, 31, v38
	v_ashrrev_i32_e32 v170, 31, v39
	v_or_b32_e32 v162, 0x80000000, v162
	v_or_b32_e32 v163, 0x80000000, v163
	v_or_b32_e32 v164, 0x80000000, v164
	v_or_b32_e32 v170, 0x80000000, v170
	v_xor_b32_e32 v36, v36, v162
	v_xor_b32_e32 v37, v37, v163
	v_xor_b32_e32 v38, v38, v164
	v_xor_b32_e32 v39, v39, v170
	s_cmp_eq_u32 s64, 1
	s_cbranch_scc0 .Ltk0_cn1
	v_cmp_lt_i32_e64 s[34:35], 0, v166
	v_cmp_lt_i32_e64 s[36:37], 1, v166
	v_cmp_lt_i32_e64 s[48:49], 2, v166
	v_cmp_lt_i32_e64 s[50:51], 3, v166
	v_cndmask_b32_e64 v36, 0, v36, s[34:35]
	v_cndmask_b32_e64 v37, 0, v37, s[36:37]
	v_cndmask_b32_e64 v38, 0, v38, s[48:49]
	v_cndmask_b32_e64 v39, 0, v39, s[50:51]
	s_branch .Ltk0_cn1
.Ltk0_cz1:
	v_mov_b32_e32 v36, 0
	v_mov_b32_e32 v37, 0
	v_mov_b32_e32 v38, 0
	v_mov_b32_e32 v39, 0
.Ltk0_cn1:
	s_cmp_le_u32 s23, 2
	s_cbranch_scc1 .Ltk0_cvd
	v_ashrrev_i32_e32 v162, 31, v40
	v_ashrrev_i32_e32 v163, 31, v41
	v_ashrrev_i32_e32 v164, 31, v42
	v_ashrrev_i32_e32 v170, 31, v43
	v_or_b32_e32 v162, 0x80000000, v162
	v_or_b32_e32 v163, 0x80000000, v163
	v_or_b32_e32 v164, 0x80000000, v164
	v_or_b32_e32 v170, 0x80000000, v170
	v_xor_b32_e32 v40, v40, v162
	v_xor_b32_e32 v41, v41, v163
	v_xor_b32_e32 v42, v42, v164
	v_xor_b32_e32 v43, v43, v170
	s_cmp_eq_u32 s64, 2
	s_cbranch_scc0 .Ltk0_cm2
	v_cmp_lt_i32_e64 s[34:35], 0, v166
	v_cmp_lt_i32_e64 s[36:37], 1, v166
	v_cmp_lt_i32_e64 s[48:49], 2, v166
	v_cmp_lt_i32_e64 s[50:51], 3, v166
	v_cndmask_b32_e64 v40, 0, v40, s[34:35]
	v_cndmask_b32_e64 v41, 0, v41, s[36:37]
	v_cndmask_b32_e64 v42, 0, v42, s[48:49]
	v_cndmask_b32_e64 v43, 0, v43, s[50:51]
.Ltk0_cm2:
	s_cmp_le_u32 s63, 3
	s_cbranch_scc1 .Ltk0_cz3
	v_ashrrev_i32_e32 v162, 31, v44
	v_ashrrev_i32_e32 v163, 31, v45
	v_ashrrev_i32_e32 v164, 31, v46
	v_ashrrev_i32_e32 v170, 31, v47
	v_or_b32_e32 v162, 0x80000000, v162
	v_or_b32_e32 v163, 0x80000000, v163
	v_or_b32_e32 v164, 0x80000000, v164
	v_or_b32_e32 v170, 0x80000000, v170
	v_xor_b32_e32 v44, v44, v162
	v_xor_b32_e32 v45, v45, v163
	v_xor_b32_e32 v46, v46, v164
	v_xor_b32_e32 v47, v47, v170
	s_cmp_eq_u32 s64, 3
	s_cbranch_scc0 .Ltk0_cn3
	v_cmp_lt_i32_e64 s[34:35], 0, v166
	v_cmp_lt_i32_e64 s[36:37], 1, v166
	v_cmp_lt_i32_e64 s[48:49], 2, v166
	v_cmp_lt_i32_e64 s[50:51], 3, v166
	v_cndmask_b32_e64 v44, 0, v44, s[34:35]
	v_cndmask_b32_e64 v45, 0, v45, s[36:37]
	v_cndmask_b32_e64 v46, 0, v46, s[48:49]
	v_cndmask_b32_e64 v47, 0, v47, s[50:51]
	s_branch .Ltk0_cn3
.Ltk0_cz3:
	v_mov_b32_e32 v44, 0
	v_mov_b32_e32 v45, 0
	v_mov_b32_e32 v46, 0
	v_mov_b32_e32 v47, 0
.Ltk0_cn3:
	s_cmp_le_u32 s23, 4
	s_cbranch_scc1 .Ltk0_cvd
	v_ashrrev_i32_e32 v162, 31, v48
	v_ashrrev_i32_e32 v163, 31, v49
	v_ashrrev_i32_e32 v164, 31, v50
	v_ashrrev_i32_e32 v170, 31, v51
	v_or_b32_e32 v162, 0x80000000, v162
	v_or_b32_e32 v163, 0x80000000, v163
	v_or_b32_e32 v164, 0x80000000, v164
	v_or_b32_e32 v170, 0x80000000, v170
	v_xor_b32_e32 v48, v48, v162
	v_xor_b32_e32 v49, v49, v163
	v_xor_b32_e32 v50, v50, v164
	v_xor_b32_e32 v51, v51, v170
	s_cmp_eq_u32 s64, 4
	s_cbranch_scc0 .Ltk0_cm4
	v_cmp_lt_i32_e64 s[34:35], 0, v166
	v_cmp_lt_i32_e64 s[36:37], 1, v166
	v_cmp_lt_i32_e64 s[48:49], 2, v166
	v_cmp_lt_i32_e64 s[50:51], 3, v166
	v_cndmask_b32_e64 v48, 0, v48, s[34:35]
	v_cndmask_b32_e64 v49, 0, v49, s[36:37]
	v_cndmask_b32_e64 v50, 0, v50, s[48:49]
	v_cndmask_b32_e64 v51, 0, v51, s[50:51]
.Ltk0_cm4:
	s_cmp_le_u32 s63, 5
	s_cbranch_scc1 .Ltk0_cz5
	v_ashrrev_i32_e32 v162, 31, v52
	v_ashrrev_i32_e32 v163, 31, v53
	v_ashrrev_i32_e32 v164, 31, v54
	v_ashrrev_i32_e32 v170, 31, v55
	v_or_b32_e32 v162, 0x80000000, v162
	v_or_b32_e32 v163, 0x80000000, v163
	v_or_b32_e32 v164, 0x80000000, v164
	v_or_b32_e32 v170, 0x80000000, v170
	v_xor_b32_e32 v52, v52, v162
	v_xor_b32_e32 v53, v53, v163
	v_xor_b32_e32 v54, v54, v164
	v_xor_b32_e32 v55, v55, v170
	s_cmp_eq_u32 s64, 5
	s_cbranch_scc0 .Ltk0_cn5
	v_cmp_lt_i32_e64 s[34:35], 0, v166
	v_cmp_lt_i32_e64 s[36:37], 1, v166
	v_cmp_lt_i32_e64 s[48:49], 2, v166
	v_cmp_lt_i32_e64 s[50:51], 3, v166
	v_cndmask_b32_e64 v52, 0, v52, s[34:35]
	v_cndmask_b32_e64 v53, 0, v53, s[36:37]
	v_cndmask_b32_e64 v54, 0, v54, s[48:49]
	v_cndmask_b32_e64 v55, 0, v55, s[50:51]
	s_branch .Ltk0_cn5
.Ltk0_cz5:
	v_mov_b32_e32 v52, 0
	v_mov_b32_e32 v53, 0
	v_mov_b32_e32 v54, 0
	v_mov_b32_e32 v55, 0
.Ltk0_cn5:
	s_cmp_le_u32 s23, 6
	s_cbranch_scc1 .Ltk0_cvd
	v_ashrrev_i32_e32 v162, 31, v56
	v_ashrrev_i32_e32 v163, 31, v57
	v_ashrrev_i32_e32 v164, 31, v58
	v_ashrrev_i32_e32 v170, 31, v59
	v_or_b32_e32 v162, 0x80000000, v162
	v_or_b32_e32 v163, 0x80000000, v163
	v_or_b32_e32 v164, 0x80000000, v164
	v_or_b32_e32 v170, 0x80000000, v170
	v_xor_b32_e32 v56, v56, v162
	v_xor_b32_e32 v57, v57, v163
	v_xor_b32_e32 v58, v58, v164
	v_xor_b32_e32 v59, v59, v170
	s_cmp_eq_u32 s64, 6
	s_cbranch_scc0 .Ltk0_cm6
	v_cmp_lt_i32_e64 s[34:35], 0, v166
	v_cmp_lt_i32_e64 s[36:37], 1, v166
	v_cmp_lt_i32_e64 s[48:49], 2, v166
	v_cmp_lt_i32_e64 s[50:51], 3, v166
	v_cndmask_b32_e64 v56, 0, v56, s[34:35]
	v_cndmask_b32_e64 v57, 0, v57, s[36:37]
	v_cndmask_b32_e64 v58, 0, v58, s[48:49]
	v_cndmask_b32_e64 v59, 0, v59, s[50:51]
.Ltk0_cm6:
	s_cmp_le_u32 s63, 7
	s_cbranch_scc1 .Ltk0_cz7
	v_ashrrev_i32_e32 v162, 31, v60
	v_ashrrev_i32_e32 v163, 31, v61
	v_ashrrev_i32_e32 v164, 31, v62
	v_ashrrev_i32_e32 v170, 31, v63
	v_or_b32_e32 v162, 0x80000000, v162
	v_or_b32_e32 v163, 0x80000000, v163
	v_or_b32_e32 v164, 0x80000000, v164
	v_or_b32_e32 v170, 0x80000000, v170
	v_xor_b32_e32 v60, v60, v162
	v_xor_b32_e32 v61, v61, v163
	v_xor_b32_e32 v62, v62, v164
	v_xor_b32_e32 v63, v63, v170
	s_cmp_eq_u32 s64, 7
	s_cbranch_scc0 .Ltk0_cn7
	v_cmp_lt_i32_e64 s[34:35], 0, v166
	v_cmp_lt_i32_e64 s[36:37], 1, v166
	v_cmp_lt_i32_e64 s[48:49], 2, v166
	v_cmp_lt_i32_e64 s[50:51], 3, v166
	v_cndmask_b32_e64 v60, 0, v60, s[34:35]
	v_cndmask_b32_e64 v61, 0, v61, s[36:37]
	v_cndmask_b32_e64 v62, 0, v62, s[48:49]
	v_cndmask_b32_e64 v63, 0, v63, s[50:51]
	s_branch .Ltk0_cn7
.Ltk0_cz7:
	v_mov_b32_e32 v60, 0
	v_mov_b32_e32 v61, 0
	v_mov_b32_e32 v62, 0
	v_mov_b32_e32 v63, 0
.Ltk0_cn7:
	s_cmp_le_u32 s23, 8
	s_cbranch_scc1 .Ltk0_cvd
	v_ashrrev_i32_e32 v162, 31, v64
	v_ashrrev_i32_e32 v163, 31, v65
	v_ashrrev_i32_e32 v164, 31, v66
	v_ashrrev_i32_e32 v170, 31, v67
	v_or_b32_e32 v162, 0x80000000, v162
	v_or_b32_e32 v163, 0x80000000, v163
	v_or_b32_e32 v164, 0x80000000, v164
	v_or_b32_e32 v170, 0x80000000, v170
	v_xor_b32_e32 v64, v64, v162
	v_xor_b32_e32 v65, v65, v163
	v_xor_b32_e32 v66, v66, v164
	v_xor_b32_e32 v67, v67, v170
	s_cmp_eq_u32 s64, 8
	s_cbranch_scc0 .Ltk0_cm8
	v_cmp_lt_i32_e64 s[34:35], 0, v166
	v_cmp_lt_i32_e64 s[36:37], 1, v166
	v_cmp_lt_i32_e64 s[48:49], 2, v166
	v_cmp_lt_i32_e64 s[50:51], 3, v166
	v_cndmask_b32_e64 v64, 0, v64, s[34:35]
	v_cndmask_b32_e64 v65, 0, v65, s[36:37]
	v_cndmask_b32_e64 v66, 0, v66, s[48:49]
	v_cndmask_b32_e64 v67, 0, v67, s[50:51]
.Ltk0_cm8:
	s_cmp_le_u32 s63, 9
	s_cbranch_scc1 .Ltk0_cz9
	v_ashrrev_i32_e32 v162, 31, v68
	v_ashrrev_i32_e32 v163, 31, v69
	v_ashrrev_i32_e32 v164, 31, v70
	v_ashrrev_i32_e32 v170, 31, v71
	v_or_b32_e32 v162, 0x80000000, v162
	v_or_b32_e32 v163, 0x80000000, v163
	v_or_b32_e32 v164, 0x80000000, v164
	v_or_b32_e32 v170, 0x80000000, v170
	v_xor_b32_e32 v68, v68, v162
	v_xor_b32_e32 v69, v69, v163
	v_xor_b32_e32 v70, v70, v164
	v_xor_b32_e32 v71, v71, v170
	s_cmp_eq_u32 s64, 9
	s_cbranch_scc0 .Ltk0_cn9
	v_cmp_lt_i32_e64 s[34:35], 0, v166
	v_cmp_lt_i32_e64 s[36:37], 1, v166
	v_cmp_lt_i32_e64 s[48:49], 2, v166
	v_cmp_lt_i32_e64 s[50:51], 3, v166
	v_cndmask_b32_e64 v68, 0, v68, s[34:35]
	v_cndmask_b32_e64 v69, 0, v69, s[36:37]
	v_cndmask_b32_e64 v70, 0, v70, s[48:49]
	v_cndmask_b32_e64 v71, 0, v71, s[50:51]
	s_branch .Ltk0_cn9
.Ltk0_cz9:
	v_mov_b32_e32 v68, 0
	v_mov_b32_e32 v69, 0
	v_mov_b32_e32 v70, 0
	v_mov_b32_e32 v71, 0
.Ltk0_cn9:
	s_cmp_le_u32 s23, 10
	s_cbranch_scc1 .Ltk0_cvd
	v_ashrrev_i32_e32 v162, 31, v72
	v_ashrrev_i32_e32 v163, 31, v73
	v_ashrrev_i32_e32 v164, 31, v74
	v_ashrrev_i32_e32 v170, 31, v75
	v_or_b32_e32 v162, 0x80000000, v162
	v_or_b32_e32 v163, 0x80000000, v163
	v_or_b32_e32 v164, 0x80000000, v164
	v_or_b32_e32 v170, 0x80000000, v170
	v_xor_b32_e32 v72, v72, v162
	v_xor_b32_e32 v73, v73, v163
	v_xor_b32_e32 v74, v74, v164
	v_xor_b32_e32 v75, v75, v170
	s_cmp_eq_u32 s64, 10
	s_cbranch_scc0 .Ltk0_cm10
	v_cmp_lt_i32_e64 s[34:35], 0, v166
	v_cmp_lt_i32_e64 s[36:37], 1, v166
	v_cmp_lt_i32_e64 s[48:49], 2, v166
	v_cmp_lt_i32_e64 s[50:51], 3, v166
	v_cndmask_b32_e64 v72, 0, v72, s[34:35]
	v_cndmask_b32_e64 v73, 0, v73, s[36:37]
	v_cndmask_b32_e64 v74, 0, v74, s[48:49]
	v_cndmask_b32_e64 v75, 0, v75, s[50:51]
.Ltk0_cm10:
	s_cmp_le_u32 s63, 11
	s_cbranch_scc1 .Ltk0_cz11
	v_ashrrev_i32_e32 v162, 31, v76
	v_ashrrev_i32_e32 v163, 31, v77
	v_ashrrev_i32_e32 v164, 31, v78
	v_ashrrev_i32_e32 v170, 31, v79
	v_or_b32_e32 v162, 0x80000000, v162
	v_or_b32_e32 v163, 0x80000000, v163
	v_or_b32_e32 v164, 0x80000000, v164
	v_or_b32_e32 v170, 0x80000000, v170
	v_xor_b32_e32 v76, v76, v162
	v_xor_b32_e32 v77, v77, v163
	v_xor_b32_e32 v78, v78, v164
	v_xor_b32_e32 v79, v79, v170
	s_cmp_eq_u32 s64, 11
	s_cbranch_scc0 .Ltk0_cn11
	v_cmp_lt_i32_e64 s[34:35], 0, v166
	v_cmp_lt_i32_e64 s[36:37], 1, v166
	v_cmp_lt_i32_e64 s[48:49], 2, v166
	v_cmp_lt_i32_e64 s[50:51], 3, v166
	v_cndmask_b32_e64 v76, 0, v76, s[34:35]
	v_cndmask_b32_e64 v77, 0, v77, s[36:37]
	v_cndmask_b32_e64 v78, 0, v78, s[48:49]
	v_cndmask_b32_e64 v79, 0, v79, s[50:51]
	s_branch .Ltk0_cn11
.Ltk0_cz11:
	v_mov_b32_e32 v76, 0
	v_mov_b32_e32 v77, 0
	v_mov_b32_e32 v78, 0
	v_mov_b32_e32 v79, 0
.Ltk0_cn11:
	s_cmp_le_u32 s23, 12
	s_cbranch_scc1 .Ltk0_cvd
	v_ashrrev_i32_e32 v162, 31, v80
	v_ashrrev_i32_e32 v163, 31, v81
	v_ashrrev_i32_e32 v164, 31, v82
	v_ashrrev_i32_e32 v170, 31, v83
	v_or_b32_e32 v162, 0x80000000, v162
	v_or_b32_e32 v163, 0x80000000, v163
	v_or_b32_e32 v164, 0x80000000, v164
	v_or_b32_e32 v170, 0x80000000, v170
	v_xor_b32_e32 v80, v80, v162
	v_xor_b32_e32 v81, v81, v163
	v_xor_b32_e32 v82, v82, v164
	v_xor_b32_e32 v83, v83, v170
	s_cmp_eq_u32 s64, 12
	s_cbranch_scc0 .Ltk0_cm12
	v_cmp_lt_i32_e64 s[34:35], 0, v166
	v_cmp_lt_i32_e64 s[36:37], 1, v166
	v_cmp_lt_i32_e64 s[48:49], 2, v166
	v_cmp_lt_i32_e64 s[50:51], 3, v166
	v_cndmask_b32_e64 v80, 0, v80, s[34:35]
	v_cndmask_b32_e64 v81, 0, v81, s[36:37]
	v_cndmask_b32_e64 v82, 0, v82, s[48:49]
	v_cndmask_b32_e64 v83, 0, v83, s[50:51]
.Ltk0_cm12:
	s_cmp_le_u32 s63, 13
	s_cbranch_scc1 .Ltk0_cz13
	v_ashrrev_i32_e32 v162, 31, v84
	v_ashrrev_i32_e32 v163, 31, v85
	v_ashrrev_i32_e32 v164, 31, v86
	v_ashrrev_i32_e32 v170, 31, v87
	v_or_b32_e32 v162, 0x80000000, v162
	v_or_b32_e32 v163, 0x80000000, v163
	v_or_b32_e32 v164, 0x80000000, v164
	v_or_b32_e32 v170, 0x80000000, v170
	v_xor_b32_e32 v84, v84, v162
	v_xor_b32_e32 v85, v85, v163
	v_xor_b32_e32 v86, v86, v164
	v_xor_b32_e32 v87, v87, v170
	s_cmp_eq_u32 s64, 13
	s_cbranch_scc0 .Ltk0_cn13
	v_cmp_lt_i32_e64 s[34:35], 0, v166
	v_cmp_lt_i32_e64 s[36:37], 1, v166
	v_cmp_lt_i32_e64 s[48:49], 2, v166
	v_cmp_lt_i32_e64 s[50:51], 3, v166
	v_cndmask_b32_e64 v84, 0, v84, s[34:35]
	v_cndmask_b32_e64 v85, 0, v85, s[36:37]
	v_cndmask_b32_e64 v86, 0, v86, s[48:49]
	v_cndmask_b32_e64 v87, 0, v87, s[50:51]
	s_branch .Ltk0_cn13
.Ltk0_cz13:
	v_mov_b32_e32 v84, 0
	v_mov_b32_e32 v85, 0
	v_mov_b32_e32 v86, 0
	v_mov_b32_e32 v87, 0
.Ltk0_cn13:
	s_cmp_le_u32 s23, 14
	s_cbranch_scc1 .Ltk0_cvd
	v_ashrrev_i32_e32 v162, 31, v88
	v_ashrrev_i32_e32 v163, 31, v89
	v_ashrrev_i32_e32 v164, 31, v90
	v_ashrrev_i32_e32 v170, 31, v91
	v_or_b32_e32 v162, 0x80000000, v162
	v_or_b32_e32 v163, 0x80000000, v163
	v_or_b32_e32 v164, 0x80000000, v164
	v_or_b32_e32 v170, 0x80000000, v170
	v_xor_b32_e32 v88, v88, v162
	v_xor_b32_e32 v89, v89, v163
	v_xor_b32_e32 v90, v90, v164
	v_xor_b32_e32 v91, v91, v170
	s_cmp_eq_u32 s64, 14
	s_cbranch_scc0 .Ltk0_cm14
	v_cmp_lt_i32_e64 s[34:35], 0, v166
	v_cmp_lt_i32_e64 s[36:37], 1, v166
	v_cmp_lt_i32_e64 s[48:49], 2, v166
	v_cmp_lt_i32_e64 s[50:51], 3, v166
	v_cndmask_b32_e64 v88, 0, v88, s[34:35]
	v_cndmask_b32_e64 v89, 0, v89, s[36:37]
	v_cndmask_b32_e64 v90, 0, v90, s[48:49]
	v_cndmask_b32_e64 v91, 0, v91, s[50:51]
.Ltk0_cm14:
	s_cmp_le_u32 s63, 15
	s_cbranch_scc1 .Ltk0_cz15
	v_ashrrev_i32_e32 v162, 31, v92
	v_ashrrev_i32_e32 v163, 31, v93
	v_ashrrev_i32_e32 v164, 31, v94
	v_ashrrev_i32_e32 v170, 31, v95
	v_or_b32_e32 v162, 0x80000000, v162
	v_or_b32_e32 v163, 0x80000000, v163
	v_or_b32_e32 v164, 0x80000000, v164
	v_or_b32_e32 v170, 0x80000000, v170
	v_xor_b32_e32 v92, v92, v162
	v_xor_b32_e32 v93, v93, v163
	v_xor_b32_e32 v94, v94, v164
	v_xor_b32_e32 v95, v95, v170
	s_cmp_eq_u32 s64, 15
	s_cbranch_scc0 .Ltk0_cn15
	v_cmp_lt_i32_e64 s[34:35], 0, v166
	v_cmp_lt_i32_e64 s[36:37], 1, v166
	v_cmp_lt_i32_e64 s[48:49], 2, v166
	v_cmp_lt_i32_e64 s[50:51], 3, v166
	v_cndmask_b32_e64 v92, 0, v92, s[34:35]
	v_cndmask_b32_e64 v93, 0, v93, s[36:37]
	v_cndmask_b32_e64 v94, 0, v94, s[48:49]
	v_cndmask_b32_e64 v95, 0, v95, s[50:51]
	s_branch .Ltk0_cn15
.Ltk0_cz15:
	v_mov_b32_e32 v92, 0
	v_mov_b32_e32 v93, 0
	v_mov_b32_e32 v94, 0
	v_mov_b32_e32 v95, 0
.Ltk0_cn15:
	s_cmp_le_u32 s23, 16
	s_cbranch_scc1 .Ltk0_cvd
	v_ashrrev_i32_e32 v162, 31, v96
	v_ashrrev_i32_e32 v163, 31, v97
	v_ashrrev_i32_e32 v164, 31, v98
	v_ashrrev_i32_e32 v170, 31, v99
	v_or_b32_e32 v162, 0x80000000, v162
	v_or_b32_e32 v163, 0x80000000, v163
	v_or_b32_e32 v164, 0x80000000, v164
	v_or_b32_e32 v170, 0x80000000, v170
	v_xor_b32_e32 v96, v96, v162
	v_xor_b32_e32 v97, v97, v163
	v_xor_b32_e32 v98, v98, v164
	v_xor_b32_e32 v99, v99, v170
	s_cmp_eq_u32 s64, 16
	s_cbranch_scc0 .Ltk0_cm16
	v_cmp_lt_i32_e64 s[34:35], 0, v166
	v_cmp_lt_i32_e64 s[36:37], 1, v166
	v_cmp_lt_i32_e64 s[48:49], 2, v166
	v_cmp_lt_i32_e64 s[50:51], 3, v166
	v_cndmask_b32_e64 v96, 0, v96, s[34:35]
	v_cndmask_b32_e64 v97, 0, v97, s[36:37]
	v_cndmask_b32_e64 v98, 0, v98, s[48:49]
	v_cndmask_b32_e64 v99, 0, v99, s[50:51]
.Ltk0_cm16:
	s_cmp_le_u32 s63, 17
	s_cbranch_scc1 .Ltk0_cz17
	v_ashrrev_i32_e32 v162, 31, v100
	v_ashrrev_i32_e32 v163, 31, v101
	v_ashrrev_i32_e32 v164, 31, v102
	v_ashrrev_i32_e32 v170, 31, v103
	v_or_b32_e32 v162, 0x80000000, v162
	v_or_b32_e32 v163, 0x80000000, v163
	v_or_b32_e32 v164, 0x80000000, v164
	v_or_b32_e32 v170, 0x80000000, v170
	v_xor_b32_e32 v100, v100, v162
	v_xor_b32_e32 v101, v101, v163
	v_xor_b32_e32 v102, v102, v164
	v_xor_b32_e32 v103, v103, v170
	s_cmp_eq_u32 s64, 17
	s_cbranch_scc0 .Ltk0_cn17
	v_cmp_lt_i32_e64 s[34:35], 0, v166
	v_cmp_lt_i32_e64 s[36:37], 1, v166
	v_cmp_lt_i32_e64 s[48:49], 2, v166
	v_cmp_lt_i32_e64 s[50:51], 3, v166
	v_cndmask_b32_e64 v100, 0, v100, s[34:35]
	v_cndmask_b32_e64 v101, 0, v101, s[36:37]
	v_cndmask_b32_e64 v102, 0, v102, s[48:49]
	v_cndmask_b32_e64 v103, 0, v103, s[50:51]
	s_branch .Ltk0_cn17
.Ltk0_cz17:
	v_mov_b32_e32 v100, 0
	v_mov_b32_e32 v101, 0
	v_mov_b32_e32 v102, 0
	v_mov_b32_e32 v103, 0
.Ltk0_cn17:
	s_cmp_le_u32 s23, 18
	s_cbranch_scc1 .Ltk0_cvd
	v_ashrrev_i32_e32 v162, 31, v104
	v_ashrrev_i32_e32 v163, 31, v105
	v_ashrrev_i32_e32 v164, 31, v106
	v_ashrrev_i32_e32 v170, 31, v107
	v_or_b32_e32 v162, 0x80000000, v162
	v_or_b32_e32 v163, 0x80000000, v163
	v_or_b32_e32 v164, 0x80000000, v164
	v_or_b32_e32 v170, 0x80000000, v170
	v_xor_b32_e32 v104, v104, v162
	v_xor_b32_e32 v105, v105, v163
	v_xor_b32_e32 v106, v106, v164
	v_xor_b32_e32 v107, v107, v170
	s_cmp_eq_u32 s64, 18
	s_cbranch_scc0 .Ltk0_cm18
	v_cmp_lt_i32_e64 s[34:35], 0, v166
	v_cmp_lt_i32_e64 s[36:37], 1, v166
	v_cmp_lt_i32_e64 s[48:49], 2, v166
	v_cmp_lt_i32_e64 s[50:51], 3, v166
	v_cndmask_b32_e64 v104, 0, v104, s[34:35]
	v_cndmask_b32_e64 v105, 0, v105, s[36:37]
	v_cndmask_b32_e64 v106, 0, v106, s[48:49]
	v_cndmask_b32_e64 v107, 0, v107, s[50:51]
.Ltk0_cm18:
	s_cmp_le_u32 s63, 19
	s_cbranch_scc1 .Ltk0_cz19
	v_ashrrev_i32_e32 v162, 31, v108
	v_ashrrev_i32_e32 v163, 31, v109
	v_ashrrev_i32_e32 v164, 31, v110
	v_ashrrev_i32_e32 v170, 31, v111
	v_or_b32_e32 v162, 0x80000000, v162
	v_or_b32_e32 v163, 0x80000000, v163
	v_or_b32_e32 v164, 0x80000000, v164
	v_or_b32_e32 v170, 0x80000000, v170
	v_xor_b32_e32 v108, v108, v162
	v_xor_b32_e32 v109, v109, v163
	v_xor_b32_e32 v110, v110, v164
	v_xor_b32_e32 v111, v111, v170
	s_cmp_eq_u32 s64, 19
	s_cbranch_scc0 .Ltk0_cn19
	v_cmp_lt_i32_e64 s[34:35], 0, v166
	v_cmp_lt_i32_e64 s[36:37], 1, v166
	v_cmp_lt_i32_e64 s[48:49], 2, v166
	v_cmp_lt_i32_e64 s[50:51], 3, v166
	v_cndmask_b32_e64 v108, 0, v108, s[34:35]
	v_cndmask_b32_e64 v109, 0, v109, s[36:37]
	v_cndmask_b32_e64 v110, 0, v110, s[48:49]
	v_cndmask_b32_e64 v111, 0, v111, s[50:51]
	s_branch .Ltk0_cn19
.Ltk0_cz19:
	v_mov_b32_e32 v108, 0
	v_mov_b32_e32 v109, 0
	v_mov_b32_e32 v110, 0
	v_mov_b32_e32 v111, 0
.Ltk0_cn19:
	s_cmp_le_u32 s23, 20
	s_cbranch_scc1 .Ltk0_cvd
	v_ashrrev_i32_e32 v162, 31, v112
	v_ashrrev_i32_e32 v163, 31, v113
	v_ashrrev_i32_e32 v164, 31, v114
	v_ashrrev_i32_e32 v170, 31, v115
	v_or_b32_e32 v162, 0x80000000, v162
	v_or_b32_e32 v163, 0x80000000, v163
	v_or_b32_e32 v164, 0x80000000, v164
	v_or_b32_e32 v170, 0x80000000, v170
	v_xor_b32_e32 v112, v112, v162
	v_xor_b32_e32 v113, v113, v163
	v_xor_b32_e32 v114, v114, v164
	v_xor_b32_e32 v115, v115, v170
	s_cmp_eq_u32 s64, 20
	s_cbranch_scc0 .Ltk0_cm20
	v_cmp_lt_i32_e64 s[34:35], 0, v166
	v_cmp_lt_i32_e64 s[36:37], 1, v166
	v_cmp_lt_i32_e64 s[48:49], 2, v166
	v_cmp_lt_i32_e64 s[50:51], 3, v166
	v_cndmask_b32_e64 v112, 0, v112, s[34:35]
	v_cndmask_b32_e64 v113, 0, v113, s[36:37]
	v_cndmask_b32_e64 v114, 0, v114, s[48:49]
	v_cndmask_b32_e64 v115, 0, v115, s[50:51]
.Ltk0_cm20:
	s_cmp_le_u32 s63, 21
	s_cbranch_scc1 .Ltk0_cz21
	v_ashrrev_i32_e32 v162, 31, v116
	v_ashrrev_i32_e32 v163, 31, v117
	v_ashrrev_i32_e32 v164, 31, v118
	v_ashrrev_i32_e32 v170, 31, v119
	v_or_b32_e32 v162, 0x80000000, v162
	v_or_b32_e32 v163, 0x80000000, v163
	v_or_b32_e32 v164, 0x80000000, v164
	v_or_b32_e32 v170, 0x80000000, v170
	v_xor_b32_e32 v116, v116, v162
	v_xor_b32_e32 v117, v117, v163
	v_xor_b32_e32 v118, v118, v164
	v_xor_b32_e32 v119, v119, v170
	s_cmp_eq_u32 s64, 21
	s_cbranch_scc0 .Ltk0_cn21
	v_cmp_lt_i32_e64 s[34:35], 0, v166
	v_cmp_lt_i32_e64 s[36:37], 1, v166
	v_cmp_lt_i32_e64 s[48:49], 2, v166
	v_cmp_lt_i32_e64 s[50:51], 3, v166
	v_cndmask_b32_e64 v116, 0, v116, s[34:35]
	v_cndmask_b32_e64 v117, 0, v117, s[36:37]
	v_cndmask_b32_e64 v118, 0, v118, s[48:49]
	v_cndmask_b32_e64 v119, 0, v119, s[50:51]
	s_branch .Ltk0_cn21
.Ltk0_cz21:
	v_mov_b32_e32 v116, 0
	v_mov_b32_e32 v117, 0
	v_mov_b32_e32 v118, 0
	v_mov_b32_e32 v119, 0
.Ltk0_cn21:
	s_cmp_le_u32 s23, 22
	s_cbranch_scc1 .Ltk0_cvd
	v_ashrrev_i32_e32 v162, 31, v120
	v_ashrrev_i32_e32 v163, 31, v121
	v_ashrrev_i32_e32 v164, 31, v122
	v_ashrrev_i32_e32 v170, 31, v123
	v_or_b32_e32 v162, 0x80000000, v162
	v_or_b32_e32 v163, 0x80000000, v163
	v_or_b32_e32 v164, 0x80000000, v164
	v_or_b32_e32 v170, 0x80000000, v170
	v_xor_b32_e32 v120, v120, v162
	v_xor_b32_e32 v121, v121, v163
	v_xor_b32_e32 v122, v122, v164
	v_xor_b32_e32 v123, v123, v170
	s_cmp_eq_u32 s64, 22
	s_cbranch_scc0 .Ltk0_cm22
	v_cmp_lt_i32_e64 s[34:35], 0, v166
	v_cmp_lt_i32_e64 s[36:37], 1, v166
	v_cmp_lt_i32_e64 s[48:49], 2, v166
	v_cmp_lt_i32_e64 s[50:51], 3, v166
	v_cndmask_b32_e64 v120, 0, v120, s[34:35]
	v_cndmask_b32_e64 v121, 0, v121, s[36:37]
	v_cndmask_b32_e64 v122, 0, v122, s[48:49]
	v_cndmask_b32_e64 v123, 0, v123, s[50:51]
.Ltk0_cm22:
	s_cmp_le_u32 s63, 23
	s_cbranch_scc1 .Ltk0_cz23
	v_ashrrev_i32_e32 v162, 31, v124
	v_ashrrev_i32_e32 v163, 31, v125
	v_ashrrev_i32_e32 v164, 31, v126
	v_ashrrev_i32_e32 v170, 31, v127
	v_or_b32_e32 v162, 0x80000000, v162
	v_or_b32_e32 v163, 0x80000000, v163
	v_or_b32_e32 v164, 0x80000000, v164
	v_or_b32_e32 v170, 0x80000000, v170
	v_xor_b32_e32 v124, v124, v162
	v_xor_b32_e32 v125, v125, v163
	v_xor_b32_e32 v126, v126, v164
	v_xor_b32_e32 v127, v127, v170
	s_cmp_eq_u32 s64, 23
	s_cbranch_scc0 .Ltk0_cn23
	v_cmp_lt_i32_e64 s[34:35], 0, v166
	v_cmp_lt_i32_e64 s[36:37], 1, v166
	v_cmp_lt_i32_e64 s[48:49], 2, v166
	v_cmp_lt_i32_e64 s[50:51], 3, v166
	v_cndmask_b32_e64 v124, 0, v124, s[34:35]
	v_cndmask_b32_e64 v125, 0, v125, s[36:37]
	v_cndmask_b32_e64 v126, 0, v126, s[48:49]
	v_cndmask_b32_e64 v127, 0, v127, s[50:51]
	s_branch .Ltk0_cn23
.Ltk0_cz23:
	v_mov_b32_e32 v124, 0
	v_mov_b32_e32 v125, 0
	v_mov_b32_e32 v126, 0
	v_mov_b32_e32 v127, 0
.Ltk0_cn23:
	s_cmp_le_u32 s23, 24
	s_cbranch_scc1 .Ltk0_cvd
	v_ashrrev_i32_e32 v162, 31, v128
	v_ashrrev_i32_e32 v163, 31, v129
	v_ashrrev_i32_e32 v164, 31, v130
	v_ashrrev_i32_e32 v170, 31, v131
	v_or_b32_e32 v162, 0x80000000, v162
	v_or_b32_e32 v163, 0x80000000, v163
	v_or_b32_e32 v164, 0x80000000, v164
	v_or_b32_e32 v170, 0x80000000, v170
	v_xor_b32_e32 v128, v128, v162
	v_xor_b32_e32 v129, v129, v163
	v_xor_b32_e32 v130, v130, v164
	v_xor_b32_e32 v131, v131, v170
	s_cmp_eq_u32 s64, 24
	s_cbranch_scc0 .Ltk0_cm24
	v_cmp_lt_i32_e64 s[34:35], 0, v166
	v_cmp_lt_i32_e64 s[36:37], 1, v166
	v_cmp_lt_i32_e64 s[48:49], 2, v166
	v_cmp_lt_i32_e64 s[50:51], 3, v166
	v_cndmask_b32_e64 v128, 0, v128, s[34:35]
	v_cndmask_b32_e64 v129, 0, v129, s[36:37]
	v_cndmask_b32_e64 v130, 0, v130, s[48:49]
	v_cndmask_b32_e64 v131, 0, v131, s[50:51]
.Ltk0_cm24:
	s_cmp_le_u32 s63, 25
	s_cbranch_scc1 .Ltk0_cz25
	v_ashrrev_i32_e32 v162, 31, v132
	v_ashrrev_i32_e32 v163, 31, v133
	v_ashrrev_i32_e32 v164, 31, v134
	v_ashrrev_i32_e32 v170, 31, v135
	v_or_b32_e32 v162, 0x80000000, v162
	v_or_b32_e32 v163, 0x80000000, v163
	v_or_b32_e32 v164, 0x80000000, v164
	v_or_b32_e32 v170, 0x80000000, v170
	v_xor_b32_e32 v132, v132, v162
	v_xor_b32_e32 v133, v133, v163
	v_xor_b32_e32 v134, v134, v164
	v_xor_b32_e32 v135, v135, v170
	s_cmp_eq_u32 s64, 25
	s_cbranch_scc0 .Ltk0_cn25
	v_cmp_lt_i32_e64 s[34:35], 0, v166
	v_cmp_lt_i32_e64 s[36:37], 1, v166
	v_cmp_lt_i32_e64 s[48:49], 2, v166
	v_cmp_lt_i32_e64 s[50:51], 3, v166
	v_cndmask_b32_e64 v132, 0, v132, s[34:35]
	v_cndmask_b32_e64 v133, 0, v133, s[36:37]
	v_cndmask_b32_e64 v134, 0, v134, s[48:49]
	v_cndmask_b32_e64 v135, 0, v135, s[50:51]
	s_branch .Ltk0_cn25
.Ltk0_cz25:
	v_mov_b32_e32 v132, 0
	v_mov_b32_e32 v133, 0
	v_mov_b32_e32 v134, 0
	v_mov_b32_e32 v135, 0
.Ltk0_cn25:
	s_cmp_le_u32 s23, 26
	s_cbranch_scc1 .Ltk0_cvd
	v_ashrrev_i32_e32 v162, 31, v136
	v_ashrrev_i32_e32 v163, 31, v137
	v_ashrrev_i32_e32 v164, 31, v138
	v_ashrrev_i32_e32 v170, 31, v139
	v_or_b32_e32 v162, 0x80000000, v162
	v_or_b32_e32 v163, 0x80000000, v163
	v_or_b32_e32 v164, 0x80000000, v164
	v_or_b32_e32 v170, 0x80000000, v170
	v_xor_b32_e32 v136, v136, v162
	v_xor_b32_e32 v137, v137, v163
	v_xor_b32_e32 v138, v138, v164
	v_xor_b32_e32 v139, v139, v170
	s_cmp_eq_u32 s64, 26
	s_cbranch_scc0 .Ltk0_cm26
	v_cmp_lt_i32_e64 s[34:35], 0, v166
	v_cmp_lt_i32_e64 s[36:37], 1, v166
	v_cmp_lt_i32_e64 s[48:49], 2, v166
	v_cmp_lt_i32_e64 s[50:51], 3, v166
	v_cndmask_b32_e64 v136, 0, v136, s[34:35]
	v_cndmask_b32_e64 v137, 0, v137, s[36:37]
	v_cndmask_b32_e64 v138, 0, v138, s[48:49]
	v_cndmask_b32_e64 v139, 0, v139, s[50:51]
.Ltk0_cm26:
	s_cmp_le_u32 s63, 27
	s_cbranch_scc1 .Ltk0_cz27
	v_ashrrev_i32_e32 v162, 31, v140
	v_ashrrev_i32_e32 v163, 31, v141
	v_ashrrev_i32_e32 v164, 31, v142
	v_ashrrev_i32_e32 v170, 31, v143
	v_or_b32_e32 v162, 0x80000000, v162
	v_or_b32_e32 v163, 0x80000000, v163
	v_or_b32_e32 v164, 0x80000000, v164
	v_or_b32_e32 v170, 0x80000000, v170
	v_xor_b32_e32 v140, v140, v162
	v_xor_b32_e32 v141, v141, v163
	v_xor_b32_e32 v142, v142, v164
	v_xor_b32_e32 v143, v143, v170
	s_cmp_eq_u32 s64, 27
	s_cbranch_scc0 .Ltk0_cn27
	v_cmp_lt_i32_e64 s[34:35], 0, v166
	v_cmp_lt_i32_e64 s[36:37], 1, v166
	v_cmp_lt_i32_e64 s[48:49], 2, v166
	v_cmp_lt_i32_e64 s[50:51], 3, v166
	v_cndmask_b32_e64 v140, 0, v140, s[34:35]
	v_cndmask_b32_e64 v141, 0, v141, s[36:37]
	v_cndmask_b32_e64 v142, 0, v142, s[48:49]
	v_cndmask_b32_e64 v143, 0, v143, s[50:51]
	s_branch .Ltk0_cn27
.Ltk0_cz27:
	v_mov_b32_e32 v140, 0
	v_mov_b32_e32 v141, 0
	v_mov_b32_e32 v142, 0
	v_mov_b32_e32 v143, 0
.Ltk0_cn27:
	s_cmp_le_u32 s23, 28
	s_cbranch_scc1 .Ltk0_cvd
	v_ashrrev_i32_e32 v162, 31, v144
	v_ashrrev_i32_e32 v163, 31, v145
	v_ashrrev_i32_e32 v164, 31, v146
	v_ashrrev_i32_e32 v170, 31, v147
	v_or_b32_e32 v162, 0x80000000, v162
	v_or_b32_e32 v163, 0x80000000, v163
	v_or_b32_e32 v164, 0x80000000, v164
	v_or_b32_e32 v170, 0x80000000, v170
	v_xor_b32_e32 v144, v144, v162
	v_xor_b32_e32 v145, v145, v163
	v_xor_b32_e32 v146, v146, v164
	v_xor_b32_e32 v147, v147, v170
	s_cmp_eq_u32 s64, 28
	s_cbranch_scc0 .Ltk0_cm28
	v_cmp_lt_i32_e64 s[34:35], 0, v166
	v_cmp_lt_i32_e64 s[36:37], 1, v166
	v_cmp_lt_i32_e64 s[48:49], 2, v166
	v_cmp_lt_i32_e64 s[50:51], 3, v166
	v_cndmask_b32_e64 v144, 0, v144, s[34:35]
	v_cndmask_b32_e64 v145, 0, v145, s[36:37]
	v_cndmask_b32_e64 v146, 0, v146, s[48:49]
	v_cndmask_b32_e64 v147, 0, v147, s[50:51]
.Ltk0_cm28:
	s_cmp_le_u32 s63, 29
	s_cbranch_scc1 .Ltk0_cz29
	v_ashrrev_i32_e32 v162, 31, v148
	v_ashrrev_i32_e32 v163, 31, v149
	v_ashrrev_i32_e32 v164, 31, v150
	v_ashrrev_i32_e32 v170, 31, v151
	v_or_b32_e32 v162, 0x80000000, v162
	v_or_b32_e32 v163, 0x80000000, v163
	v_or_b32_e32 v164, 0x80000000, v164
	v_or_b32_e32 v170, 0x80000000, v170
	v_xor_b32_e32 v148, v148, v162
	v_xor_b32_e32 v149, v149, v163
	v_xor_b32_e32 v150, v150, v164
	v_xor_b32_e32 v151, v151, v170
	s_cmp_eq_u32 s64, 29
	s_cbranch_scc0 .Ltk0_cn29
	v_cmp_lt_i32_e64 s[34:35], 0, v166
	v_cmp_lt_i32_e64 s[36:37], 1, v166
	v_cmp_lt_i32_e64 s[48:49], 2, v166
	v_cmp_lt_i32_e64 s[50:51], 3, v166
	v_cndmask_b32_e64 v148, 0, v148, s[34:35]
	v_cndmask_b32_e64 v149, 0, v149, s[36:37]
	v_cndmask_b32_e64 v150, 0, v150, s[48:49]
	v_cndmask_b32_e64 v151, 0, v151, s[50:51]
	s_branch .Ltk0_cn29
.Ltk0_cz29:
	v_mov_b32_e32 v148, 0
	v_mov_b32_e32 v149, 0
	v_mov_b32_e32 v150, 0
	v_mov_b32_e32 v151, 0
.Ltk0_cn29:
	s_cmp_le_u32 s23, 30
	s_cbranch_scc1 .Ltk0_cvd
	v_ashrrev_i32_e32 v162, 31, v152
	v_ashrrev_i32_e32 v163, 31, v153
	v_ashrrev_i32_e32 v164, 31, v154
	v_ashrrev_i32_e32 v170, 31, v155
	v_or_b32_e32 v162, 0x80000000, v162
	v_or_b32_e32 v163, 0x80000000, v163
	v_or_b32_e32 v164, 0x80000000, v164
	v_or_b32_e32 v170, 0x80000000, v170
	v_xor_b32_e32 v152, v152, v162
	v_xor_b32_e32 v153, v153, v163
	v_xor_b32_e32 v154, v154, v164
	v_xor_b32_e32 v155, v155, v170
	s_cmp_eq_u32 s64, 30
	s_cbranch_scc0 .Ltk0_cm30
	v_cmp_lt_i32_e64 s[34:35], 0, v166
	v_cmp_lt_i32_e64 s[36:37], 1, v166
	v_cmp_lt_i32_e64 s[48:49], 2, v166
	v_cmp_lt_i32_e64 s[50:51], 3, v166
	v_cndmask_b32_e64 v152, 0, v152, s[34:35]
	v_cndmask_b32_e64 v153, 0, v153, s[36:37]
	v_cndmask_b32_e64 v154, 0, v154, s[48:49]
	v_cndmask_b32_e64 v155, 0, v155, s[50:51]
.Ltk0_cm30:
	s_cmp_le_u32 s63, 31
	s_cbranch_scc1 .Ltk0_cz31
	v_ashrrev_i32_e32 v162, 31, v156
	v_ashrrev_i32_e32 v163, 31, v157
	v_ashrrev_i32_e32 v164, 31, v158
	v_ashrrev_i32_e32 v170, 31, v159
	v_or_b32_e32 v162, 0x80000000, v162
	v_or_b32_e32 v163, 0x80000000, v163
	v_or_b32_e32 v164, 0x80000000, v164
	v_or_b32_e32 v170, 0x80000000, v170
	v_xor_b32_e32 v156, v156, v162
	v_xor_b32_e32 v157, v157, v163
	v_xor_b32_e32 v158, v158, v164
	v_xor_b32_e32 v159, v159, v170
	s_cmp_eq_u32 s64, 31
	s_cbranch_scc0 .Ltk0_cn31
	v_cmp_lt_i32_e64 s[34:35], 0, v166
	v_cmp_lt_i32_e64 s[36:37], 1, v166
	v_cmp_lt_i32_e64 s[48:49], 2, v166
	v_cmp_lt_i32_e64 s[50:51], 3, v166
	v_cndmask_b32_e64 v156, 0, v156, s[34:35]
	v_cndmask_b32_e64 v157, 0, v157, s[36:37]
	v_cndmask_b32_e64 v158, 0, v158, s[48:49]
	v_cndmask_b32_e64 v159, 0, v159, s[50:51]
	s_branch .Ltk0_cn31
.Ltk0_cz31:
	v_mov_b32_e32 v156, 0
	v_mov_b32_e32 v157, 0
	v_mov_b32_e32 v158, 0
	v_mov_b32_e32 v159, 0
.Ltk0_cn31:
.Ltk0_cvd:
.Ltk0_binit:
	s_mov_b32 s20, 0
	s_brev_b32 s21, 1
.Ltk0_bloop:
	s_or_b32 s30, s20, s21
	v_mov_b32_e32 v160, 0
	v_mov_b32_e32 v161, 0
	v_cmp_le_u32_e64 s[34:35], s30, v32
	v_cmp_le_u32_e64 s[36:37], s30, v33
	v_cmp_le_u32_e64 s[48:49], s30, v34
	v_addc_co_u32_e64 v160, vcc, 0, v160, s[34:35]
	v_cmp_le_u32_e64 s[50:51], s30, v35
	v_addc_co_u32_e64 v161, vcc, 0, v161, s[36:37]
	v_cmp_le_u32_e64 s[34:35], s30, v36
	v_addc_co_u32_e64 v160, vcc, 0, v160, s[48:49]
	v_cmp_le_u32_e64 s[36:37], s30, v37
	v_addc_co_u32_e64 v161, vcc, 0, v161, s[50:51]
	v_cmp_le_u32_e64 s[48:49], s30, v38
	v_addc_co_u32_e64 v160, vcc, 0, v160, s[34:35]
	v_cmp_le_u32_e64 s[50:51], s30, v39
	v_addc_co_u32_e64 v161, vcc, 0, v161, s[36:37]
	v_addc_co_u32_e64 v160, vcc, 0, v160, s[48:49]
	v_addc_co_u32_e64 v161, vcc, 0, v161, s[50:51]
	s_cmp_le_u32 s23, 2
	s_cbranch_scc1 .Ltk0_bred
	v_cmp_le_u32_e64 s[34:35], s30, v40
	v_cmp_le_u32_e64 s[36:37], s30, v41
	v_cmp_le_u32_e64 s[48:49], s30, v42
	v_addc_co_u32_e64 v160, vcc, 0, v160, s[34:35]
	v_cmp_le_u32_e64 s[50:51], s30, v43
	v_addc_co_u32_e64 v161, vcc, 0, v161, s[36:37]
	v_cmp_le_u32_e64 s[34:35], s30, v44
	v_addc_co_u32_e64 v160, vcc, 0, v160, s[48:49]
	v_cmp_le_u32_e64 s[36:37], s30, v45
	v_addc_co_u32_e64 v161, vcc, 0, v161, s[50:51]
	v_cmp_le_u32_e64 s[48:49], s30, v46
	v_addc_co_u32_e64 v160, vcc, 0, v160, s[34:35]
	v_cmp_le_u32_e64 s[50:51], s30, v47
	v_addc_co_u32_e64 v161, vcc, 0, v161, s[36:37]
	v_addc_co_u32_e64 v160, vcc, 0, v160, s[48:49]
	v_addc_co_u32_e64 v161, vcc, 0, v161, s[50:51]
	s_cmp_le_u32 s23, 4
	s_cbranch_scc1 .Ltk0_bred
	v_cmp_le_u32_e64 s[34:35], s30, v48
	v_cmp_le_u32_e64 s[36:37], s30, v49
	v_cmp_le_u32_e64 s[48:49], s30, v50
	v_addc_co_u32_e64 v160, vcc, 0, v160, s[34:35]
	v_cmp_le_u32_e64 s[50:51], s30, v51
	v_addc_co_u32_e64 v161, vcc, 0, v161, s[36:37]
	v_cmp_le_u32_e64 s[34:35], s30, v52
	v_addc_co_u32_e64 v160, vcc, 0, v160, s[48:49]
	v_cmp_le_u32_e64 s[36:37], s30, v53
	v_addc_co_u32_e64 v161, vcc, 0, v161, s[50:51]
	v_cmp_le_u32_e64 s[48:49], s30, v54
	v_addc_co_u32_e64 v160, vcc, 0, v160, s[34:35]
	v_cmp_le_u32_e64 s[50:51], s30, v55
	v_addc_co_u32_e64 v161, vcc, 0, v161, s[36:37]
	v_addc_co_u32_e64 v160, vcc, 0, v160, s[48:49]
	v_addc_co_u32_e64 v161, vcc, 0, v161, s[50:51]
	s_cmp_le_u32 s23, 6
	s_cbranch_scc1 .Ltk0_bred
	v_cmp_le_u32_e64 s[34:35], s30, v56
	v_cmp_le_u32_e64 s[36:37], s30, v57
	v_cmp_le_u32_e64 s[48:49], s30, v58
	v_addc_co_u32_e64 v160, vcc, 0, v160, s[34:35]
	v_cmp_le_u32_e64 s[50:51], s30, v59
	v_addc_co_u32_e64 v161, vcc, 0, v161, s[36:37]
	v_cmp_le_u32_e64 s[34:35], s30, v60
	v_addc_co_u32_e64 v160, vcc, 0, v160, s[48:49]
	v_cmp_le_u32_e64 s[36:37], s30, v61
	v_addc_co_u32_e64 v161, vcc, 0, v161, s[50:51]
	v_cmp_le_u32_e64 s[48:49], s30, v62
	v_addc_co_u32_e64 v160, vcc, 0, v160, s[34:35]
	v_cmp_le_u32_e64 s[50:51], s30, v63
	v_addc_co_u32_e64 v161, vcc, 0, v161, s[36:37]
	v_addc_co_u32_e64 v160, vcc, 0, v160, s[48:49]
	v_addc_co_u32_e64 v161, vcc, 0, v161, s[50:51]
	s_cmp_le_u32 s23, 8
	s_cbranch_scc1 .Ltk0_bred
	v_cmp_le_u32_e64 s[34:35], s30, v64
	v_cmp_le_u32_e64 s[36:37], s30, v65
	v_cmp_le_u32_e64 s[48:49], s30, v66
	v_addc_co_u32_e64 v160, vcc, 0, v160, s[34:35]
	v_cmp_le_u32_e64 s[50:51], s30, v67
	v_addc_co_u32_e64 v161, vcc, 0, v161, s[36:37]
	v_cmp_le_u32_e64 s[34:35], s30, v68
	v_addc_co_u32_e64 v160, vcc, 0, v160, s[48:49]
	v_cmp_le_u32_e64 s[36:37], s30, v69
	v_addc_co_u32_e64 v161, vcc, 0, v161, s[50:51]
	v_cmp_le_u32_e64 s[48:49], s30, v70
	v_addc_co_u32_e64 v160, vcc, 0, v160, s[34:35]
	v_cmp_le_u32_e64 s[50:51], s30, v71
	v_addc_co_u32_e64 v161, vcc, 0, v161, s[36:37]
	v_addc_co_u32_e64 v160, vcc, 0, v160, s[48:49]
	v_addc_co_u32_e64 v161, vcc, 0, v161, s[50:51]
	s_cmp_le_u32 s23, 10
	s_cbranch_scc1 .Ltk0_bred
	v_cmp_le_u32_e64 s[34:35], s30, v72
	v_cmp_le_u32_e64 s[36:37], s30, v73
	v_cmp_le_u32_e64 s[48:49], s30, v74
	v_addc_co_u32_e64 v160, vcc, 0, v160, s[34:35]
	v_cmp_le_u32_e64 s[50:51], s30, v75
	v_addc_co_u32_e64 v161, vcc, 0, v161, s[36:37]
	v_cmp_le_u32_e64 s[34:35], s30, v76
	v_addc_co_u32_e64 v160, vcc, 0, v160, s[48:49]
	v_cmp_le_u32_e64 s[36:37], s30, v77
	v_addc_co_u32_e64 v161, vcc, 0, v161, s[50:51]
	v_cmp_le_u32_e64 s[48:49], s30, v78
	v_addc_co_u32_e64 v160, vcc, 0, v160, s[34:35]
	v_cmp_le_u32_e64 s[50:51], s30, v79
	v_addc_co_u32_e64 v161, vcc, 0, v161, s[36:37]
	v_addc_co_u32_e64 v160, vcc, 0, v160, s[48:49]
	v_addc_co_u32_e64 v161, vcc, 0, v161, s[50:51]
	s_cmp_le_u32 s23, 12
	s_cbranch_scc1 .Ltk0_bred
	v_cmp_le_u32_e64 s[34:35], s30, v80
	v_cmp_le_u32_e64 s[36:37], s30, v81
	v_cmp_le_u32_e64 s[48:49], s30, v82
	v_addc_co_u32_e64 v160, vcc, 0, v160, s[34:35]
	v_cmp_le_u32_e64 s[50:51], s30, v83
	v_addc_co_u32_e64 v161, vcc, 0, v161, s[36:37]
	v_cmp_le_u32_e64 s[34:35], s30, v84
	v_addc_co_u32_e64 v160, vcc, 0, v160, s[48:49]
	v_cmp_le_u32_e64 s[36:37], s30, v85
	v_addc_co_u32_e64 v161, vcc, 0, v161, s[50:51]
	v_cmp_le_u32_e64 s[48:49], s30, v86
	v_addc_co_u32_e64 v160, vcc, 0, v160, s[34:35]
	v_cmp_le_u32_e64 s[50:51], s30, v87
	v_addc_co_u32_e64 v161, vcc, 0, v161, s[36:37]
	v_addc_co_u32_e64 v160, vcc, 0, v160, s[48:49]
	v_addc_co_u32_e64 v161, vcc, 0, v161, s[50:51]
	s_cmp_le_u32 s23, 14
	s_cbranch_scc1 .Ltk0_bred
	v_cmp_le_u32_e64 s[34:35], s30, v88
	v_cmp_le_u32_e64 s[36:37], s30, v89
	v_cmp_le_u32_e64 s[48:49], s30, v90
	v_addc_co_u32_e64 v160, vcc, 0, v160, s[34:35]
	v_cmp_le_u32_e64 s[50:51], s30, v91
	v_addc_co_u32_e64 v161, vcc, 0, v161, s[36:37]
	v_cmp_le_u32_e64 s[34:35], s30, v92
	v_addc_co_u32_e64 v160, vcc, 0, v160, s[48:49]
	v_cmp_le_u32_e64 s[36:37], s30, v93
	v_addc_co_u32_e64 v161, vcc, 0, v161, s[50:51]
	v_cmp_le_u32_e64 s[48:49], s30, v94
	v_addc_co_u32_e64 v160, vcc, 0, v160, s[34:35]
	v_cmp_le_u32_e64 s[50:51], s30, v95
	v_addc_co_u32_e64 v161, vcc, 0, v161, s[36:37]
	v_addc_co_u32_e64 v160, vcc, 0, v160, s[48:49]
	v_addc_co_u32_e64 v161, vcc, 0, v161, s[50:51]
	s_cmp_le_u32 s23, 16
	s_cbranch_scc1 .Ltk0_bred
	v_cmp_le_u32_e64 s[34:35], s30, v96
	v_cmp_le_u32_e64 s[36:37], s30, v97
	v_cmp_le_u32_e64 s[48:49], s30, v98
	v_addc_co_u32_e64 v160, vcc, 0, v160, s[34:35]
	v_cmp_le_u32_e64 s[50:51], s30, v99
	v_addc_co_u32_e64 v161, vcc, 0, v161, s[36:37]
	v_cmp_le_u32_e64 s[34:35], s30, v100
	v_addc_co_u32_e64 v160, vcc, 0, v160, s[48:49]
	v_cmp_le_u32_e64 s[36:37], s30, v101
	v_addc_co_u32_e64 v161, vcc, 0, v161, s[50:51]
	v_cmp_le_u32_e64 s[48:49], s30, v102
	v_addc_co_u32_e64 v160, vcc, 0, v160, s[34:35]
	v_cmp_le_u32_e64 s[50:51], s30, v103
	v_addc_co_u32_e64 v161, vcc, 0, v161, s[36:37]
	v_addc_co_u32_e64 v160, vcc, 0, v160, s[48:49]
	v_addc_co_u32_e64 v161, vcc, 0, v161, s[50:51]
	s_cmp_le_u32 s23, 18
	s_cbranch_scc1 .Ltk0_bred
	v_cmp_le_u32_e64 s[34:35], s30, v104
	v_cmp_le_u32_e64 s[36:37], s30, v105
	v_cmp_le_u32_e64 s[48:49], s30, v106
	v_addc_co_u32_e64 v160, vcc, 0, v160, s[34:35]
	v_cmp_le_u32_e64 s[50:51], s30, v107
	v_addc_co_u32_e64 v161, vcc, 0, v161, s[36:37]
	v_cmp_le_u32_e64 s[34:35], s30, v108
	v_addc_co_u32_e64 v160, vcc, 0, v160, s[48:49]
	v_cmp_le_u32_e64 s[36:37], s30, v109
	v_addc_co_u32_e64 v161, vcc, 0, v161, s[50:51]
	v_cmp_le_u32_e64 s[48:49], s30, v110
	v_addc_co_u32_e64 v160, vcc, 0, v160, s[34:35]
	v_cmp_le_u32_e64 s[50:51], s30, v111
	v_addc_co_u32_e64 v161, vcc, 0, v161, s[36:37]
	v_addc_co_u32_e64 v160, vcc, 0, v160, s[48:49]
	v_addc_co_u32_e64 v161, vcc, 0, v161, s[50:51]
	s_cmp_le_u32 s23, 20
	s_cbranch_scc1 .Ltk0_bred
	v_cmp_le_u32_e64 s[34:35], s30, v112
	v_cmp_le_u32_e64 s[36:37], s30, v113
	v_cmp_le_u32_e64 s[48:49], s30, v114
	v_addc_co_u32_e64 v160, vcc, 0, v160, s[34:35]
	v_cmp_le_u32_e64 s[50:51], s30, v115
	v_addc_co_u32_e64 v161, vcc, 0, v161, s[36:37]
	v_cmp_le_u32_e64 s[34:35], s30, v116
	v_addc_co_u32_e64 v160, vcc, 0, v160, s[48:49]
	v_cmp_le_u32_e64 s[36:37], s30, v117
	v_addc_co_u32_e64 v161, vcc, 0, v161, s[50:51]
	v_cmp_le_u32_e64 s[48:49], s30, v118
	v_addc_co_u32_e64 v160, vcc, 0, v160, s[34:35]
	v_cmp_le_u32_e64 s[50:51], s30, v119
	v_addc_co_u32_e64 v161, vcc, 0, v161, s[36:37]
	v_addc_co_u32_e64 v160, vcc, 0, v160, s[48:49]
	v_addc_co_u32_e64 v161, vcc, 0, v161, s[50:51]
	s_cmp_le_u32 s23, 22
	s_cbranch_scc1 .Ltk0_bred
	v_cmp_le_u32_e64 s[34:35], s30, v120
	v_cmp_le_u32_e64 s[36:37], s30, v121
	v_cmp_le_u32_e64 s[48:49], s30, v122
	v_addc_co_u32_e64 v160, vcc, 0, v160, s[34:35]
	v_cmp_le_u32_e64 s[50:51], s30, v123
	v_addc_co_u32_e64 v161, vcc, 0, v161, s[36:37]
	v_cmp_le_u32_e64 s[34:35], s30, v124
	v_addc_co_u32_e64 v160, vcc, 0, v160, s[48:49]
	v_cmp_le_u32_e64 s[36:37], s30, v125
	v_addc_co_u32_e64 v161, vcc, 0, v161, s[50:51]
	v_cmp_le_u32_e64 s[48:49], s30, v126
	v_addc_co_u32_e64 v160, vcc, 0, v160, s[34:35]
	v_cmp_le_u32_e64 s[50:51], s30, v127
	v_addc_co_u32_e64 v161, vcc, 0, v161, s[36:37]
	v_addc_co_u32_e64 v160, vcc, 0, v160, s[48:49]
	v_addc_co_u32_e64 v161, vcc, 0, v161, s[50:51]
	s_cmp_le_u32 s23, 24
	s_cbranch_scc1 .Ltk0_bred
	v_cmp_le_u32_e64 s[34:35], s30, v128
	v_cmp_le_u32_e64 s[36:37], s30, v129
	v_cmp_le_u32_e64 s[48:49], s30, v130
	v_addc_co_u32_e64 v160, vcc, 0, v160, s[34:35]
	v_cmp_le_u32_e64 s[50:51], s30, v131
	v_addc_co_u32_e64 v161, vcc, 0, v161, s[36:37]
	v_cmp_le_u32_e64 s[34:35], s30, v132
	v_addc_co_u32_e64 v160, vcc, 0, v160, s[48:49]
	v_cmp_le_u32_e64 s[36:37], s30, v133
	v_addc_co_u32_e64 v161, vcc, 0, v161, s[50:51]
	v_cmp_le_u32_e64 s[48:49], s30, v134
	v_addc_co_u32_e64 v160, vcc, 0, v160, s[34:35]
	v_cmp_le_u32_e64 s[50:51], s30, v135
	v_addc_co_u32_e64 v161, vcc, 0, v161, s[36:37]
	v_addc_co_u32_e64 v160, vcc, 0, v160, s[48:49]
	v_addc_co_u32_e64 v161, vcc, 0, v161, s[50:51]
	s_cmp_le_u32 s23, 26
	s_cbranch_scc1 .Ltk0_bred
	v_cmp_le_u32_e64 s[34:35], s30, v136
	v_cmp_le_u32_e64 s[36:37], s30, v137
	v_cmp_le_u32_e64 s[48:49], s30, v138
	v_addc_co_u32_e64 v160, vcc, 0, v160, s[34:35]
	v_cmp_le_u32_e64 s[50:51], s30, v139
	v_addc_co_u32_e64 v161, vcc, 0, v161, s[36:37]
	v_cmp_le_u32_e64 s[34:35], s30, v140
	v_addc_co_u32_e64 v160, vcc, 0, v160, s[48:49]
	v_cmp_le_u32_e64 s[36:37], s30, v141
	v_addc_co_u32_e64 v161, vcc, 0, v161, s[50:51]
	v_cmp_le_u32_e64 s[48:49], s30, v142
	v_addc_co_u32_e64 v160, vcc, 0, v160, s[34:35]
	v_cmp_le_u32_e64 s[50:51], s30, v143
	v_addc_co_u32_e64 v161, vcc, 0, v161, s[36:37]
	v_addc_co_u32_e64 v160, vcc, 0, v160, s[48:49]
	v_addc_co_u32_e64 v161, vcc, 0, v161, s[50:51]
	s_cmp_le_u32 s23, 28
	s_cbranch_scc1 .Ltk0_bred
	v_cmp_le_u32_e64 s[34:35], s30, v144
	v_cmp_le_u32_e64 s[36:37], s30, v145
	v_cmp_le_u32_e64 s[48:49], s30, v146
	v_addc_co_u32_e64 v160, vcc, 0, v160, s[34:35]
	v_cmp_le_u32_e64 s[50:51], s30, v147
	v_addc_co_u32_e64 v161, vcc, 0, v161, s[36:37]
	v_cmp_le_u32_e64 s[34:35], s30, v148
	v_addc_co_u32_e64 v160, vcc, 0, v160, s[48:49]
	v_cmp_le_u32_e64 s[36:37], s30, v149
	v_addc_co_u32_e64 v161, vcc, 0, v161, s[50:51]
	v_cmp_le_u32_e64 s[48:49], s30, v150
	v_addc_co_u32_e64 v160, vcc, 0, v160, s[34:35]
	v_cmp_le_u32_e64 s[50:51], s30, v151
	v_addc_co_u32_e64 v161, vcc, 0, v161, s[36:37]
	v_addc_co_u32_e64 v160, vcc, 0, v160, s[48:49]
	v_addc_co_u32_e64 v161, vcc, 0, v161, s[50:51]
	s_cmp_le_u32 s23, 30
	s_cbranch_scc1 .Ltk0_bred
	v_cmp_le_u32_e64 s[34:35], s30, v152
	v_cmp_le_u32_e64 s[36:37], s30, v153
	v_cmp_le_u32_e64 s[48:49], s30, v154
	v_addc_co_u32_e64 v160, vcc, 0, v160, s[34:35]
	v_cmp_le_u32_e64 s[50:51], s30, v155
	v_addc_co_u32_e64 v161, vcc, 0, v161, s[36:37]
	v_cmp_le_u32_e64 s[34:35], s30, v156
	v_addc_co_u32_e64 v160, vcc, 0, v160, s[48:49]
	v_cmp_le_u32_e64 s[36:37], s30, v157
	v_addc_co_u32_e64 v161, vcc, 0, v161, s[50:51]
	v_cmp_le_u32_e64 s[48:49], s30, v158
	v_addc_co_u32_e64 v160, vcc, 0, v160, s[34:35]
	v_cmp_le_u32_e64 s[50:51], s30, v159
	v_addc_co_u32_e64 v161, vcc, 0, v161, s[36:37]
	v_addc_co_u32_e64 v160, vcc, 0, v160, s[48:49]
	v_addc_co_u32_e64 v161, vcc, 0, v161, s[50:51]
.Ltk0_bred:
	v_add_u32_e32 v160, v160, v161
	s_nop 1
	v_add_u32_dpp v160, v160, v160 quad_perm:[1,0,3,2] row_mask:0xf bank_mask:0xf
	s_nop 1
	v_add_u32_dpp v160, v160, v160 quad_perm:[2,3,0,1] row_mask:0xf bank_mask:0xf
	s_nop 1
	v_add_u32_dpp v160, v160, v160 row_half_mirror row_mask:0xf bank_mask:0xf
	s_nop 1
	v_add_u32_dpp v160, v160, v160 row_mirror row_mask:0xf bank_mask:0xf
	s_nop 1
	v_readlane_b32 s31, v160, 0
	v_readlane_b32 s82, v160, 16
	v_readlane_b32 s83, v160, 32
	v_readlane_b32 s93, v160, 48
	s_nop 3
	s_add_i32 s31, s31, s82
	s_add_i32 s83, s83, s93
	s_add_i32 s31, s31, s83
	s_cmpk_eq_u32 s31, 0x100
	s_cbranch_scc1 .Ltk0_emit
	s_cmpk_ge_u32 s31, 0x100
	s_cselect_b32 s20, s30, s20
	s_lshr_b32 s21, s21, 1
	s_cmp_lg_u32 s21, 0
	s_cbranch_scc1 .Ltk0_bloop
	s_cmp_eq_u32 s62, 0
	s_cbranch_scc0 .Ltk0_epre
	s_mov_b32 s62, 1
	v_cmp_lt_u32_e64 s[34:35], s20, v32
	v_cmp_eq_u32_e64 s[36:37], s20, v32
	v_cmp_lt_u32_e64 s[48:49], s20, v33
	v_cmp_eq_u32_e64 s[50:51], s20, v33
	v_subrev_u32_e32 v162, 0, v169
	v_subrev_u32_e32 v163, 1, v169
	v_cndmask_b32_e64 v162, 0, v162, s[36:37]
	v_cndmask_b32_e64 v163, 0, v163, s[50:51]
	v_cndmask_b32_e64 v32, v162, -1, s[34:35]
	v_cndmask_b32_e64 v33, v163, -1, s[48:49]
	v_cmp_lt_u32_e64 s[34:35], s20, v34
	v_cmp_eq_u32_e64 s[36:37], s20, v34
	v_cmp_lt_u32_e64 s[48:49], s20, v35
	v_cmp_eq_u32_e64 s[50:51], s20, v35
	v_subrev_u32_e32 v162, 2, v169
	v_subrev_u32_e32 v163, 3, v169
	v_cndmask_b32_e64 v162, 0, v162, s[36:37]
	v_cndmask_b32_e64 v163, 0, v163, s[50:51]
	v_cndmask_b32_e64 v34, v162, -1, s[34:35]
	v_cndmask_b32_e64 v35, v163, -1, s[48:49]
	v_cmp_lt_u32_e64 s[34:35], s20, v36
	v_cmp_eq_u32_e64 s[36:37], s20, v36
	v_cmp_lt_u32_e64 s[48:49], s20, v37
	v_cmp_eq_u32_e64 s[50:51], s20, v37
	v_subrev_u32_e32 v162, 0x100, v169
	v_subrev_u32_e32 v163, 0x101, v169
	v_cndmask_b32_e64 v162, 0, v162, s[36:37]
	v_cndmask_b32_e64 v163, 0, v163, s[50:51]
	v_cndmask_b32_e64 v36, v162, -1, s[34:35]
	v_cndmask_b32_e64 v37, v163, -1, s[48:49]
	v_cmp_lt_u32_e64 s[34:35], s20, v38
	v_cmp_eq_u32_e64 s[36:37], s20, v38
	v_cmp_lt_u32_e64 s[48:49], s20, v39
	v_cmp_eq_u32_e64 s[50:51], s20, v39
	v_subrev_u32_e32 v162, 0x102, v169
	v_subrev_u32_e32 v163, 0x103, v169
	v_cndmask_b32_e64 v162, 0, v162, s[36:37]
	v_cndmask_b32_e64 v163, 0, v163, s[50:51]
	v_cndmask_b32_e64 v38, v162, -1, s[34:35]
	v_cndmask_b32_e64 v39, v163, -1, s[48:49]
	s_cmp_le_u32 s23, 2
	s_cbranch_scc1 .Ltk0_binit
	v_cmp_lt_u32_e64 s[34:35], s20, v40
	v_cmp_eq_u32_e64 s[36:37], s20, v40
	v_cmp_lt_u32_e64 s[48:49], s20, v41
	v_cmp_eq_u32_e64 s[50:51], s20, v41
	v_subrev_u32_e32 v162, 0x200, v169
	v_subrev_u32_e32 v163, 0x201, v169
	v_cndmask_b32_e64 v162, 0, v162, s[36:37]
	v_cndmask_b32_e64 v163, 0, v163, s[50:51]
	v_cndmask_b32_e64 v40, v162, -1, s[34:35]
	v_cndmask_b32_e64 v41, v163, -1, s[48:49]
	v_cmp_lt_u32_e64 s[34:35], s20, v42
	v_cmp_eq_u32_e64 s[36:37], s20, v42
	v_cmp_lt_u32_e64 s[48:49], s20, v43
	v_cmp_eq_u32_e64 s[50:51], s20, v43
	v_subrev_u32_e32 v162, 0x202, v169
	v_subrev_u32_e32 v163, 0x203, v169
	v_cndmask_b32_e64 v162, 0, v162, s[36:37]
	v_cndmask_b32_e64 v163, 0, v163, s[50:51]
	v_cndmask_b32_e64 v42, v162, -1, s[34:35]
	v_cndmask_b32_e64 v43, v163, -1, s[48:49]
	v_cmp_lt_u32_e64 s[34:35], s20, v44
	v_cmp_eq_u32_e64 s[36:37], s20, v44
	v_cmp_lt_u32_e64 s[48:49], s20, v45
	v_cmp_eq_u32_e64 s[50:51], s20, v45
	v_subrev_u32_e32 v162, 0x300, v169
	v_subrev_u32_e32 v163, 0x301, v169
	v_cndmask_b32_e64 v162, 0, v162, s[36:37]
	v_cndmask_b32_e64 v163, 0, v163, s[50:51]
	v_cndmask_b32_e64 v44, v162, -1, s[34:35]
	v_cndmask_b32_e64 v45, v163, -1, s[48:49]
	v_cmp_lt_u32_e64 s[34:35], s20, v46
	v_cmp_eq_u32_e64 s[36:37], s20, v46
	v_cmp_lt_u32_e64 s[48:49], s20, v47
	v_cmp_eq_u32_e64 s[50:51], s20, v47
	v_subrev_u32_e32 v162, 0x302, v169
	v_subrev_u32_e32 v163, 0x303, v169
	v_cndmask_b32_e64 v162, 0, v162, s[36:37]
	v_cndmask_b32_e64 v163, 0, v163, s[50:51]
	v_cndmask_b32_e64 v46, v162, -1, s[34:35]
	v_cndmask_b32_e64 v47, v163, -1, s[48:49]
	s_cmp_le_u32 s23, 4
	s_cbranch_scc1 .Ltk0_binit
	v_cmp_lt_u32_e64 s[34:35], s20, v48
	v_cmp_eq_u32_e64 s[36:37], s20, v48
	v_cmp_lt_u32_e64 s[48:49], s20, v49
	v_cmp_eq_u32_e64 s[50:51], s20, v49
	v_subrev_u32_e32 v162, 0x400, v169
	v_subrev_u32_e32 v163, 0x401, v169
	v_cndmask_b32_e64 v162, 0, v162, s[36:37]
	v_cndmask_b32_e64 v163, 0, v163, s[50:51]
	v_cndmask_b32_e64 v48, v162, -1, s[34:35]
	v_cndmask_b32_e64 v49, v163, -1, s[48:49]
	v_cmp_lt_u32_e64 s[34:35], s20, v50
	v_cmp_eq_u32_e64 s[36:37], s20, v50
	v_cmp_lt_u32_e64 s[48:49], s20, v51
	v_cmp_eq_u32_e64 s[50:51], s20, v51
	v_subrev_u32_e32 v162, 0x402, v169
	v_subrev_u32_e32 v163, 0x403, v169
	v_cndmask_b32_e64 v162, 0, v162, s[36:37]
	v_cndmask_b32_e64 v163, 0, v163, s[50:51]
	v_cndmask_b32_e64 v50, v162, -1, s[34:35]
	v_cndmask_b32_e64 v51, v163, -1, s[48:49]
	v_cmp_lt_u32_e64 s[34:35], s20, v52
	v_cmp_eq_u32_e64 s[36:37], s20, v52
	v_cmp_lt_u32_e64 s[48:49], s20, v53
	v_cmp_eq_u32_e64 s[50:51], s20, v53
	v_subrev_u32_e32 v162, 0x500, v169
	v_subrev_u32_e32 v163, 0x501, v169
	v_cndmask_b32_e64 v162, 0, v162, s[36:37]
	v_cndmask_b32_e64 v163, 0, v163, s[50:51]
	v_cndmask_b32_e64 v52, v162, -1, s[34:35]
	v_cndmask_b32_e64 v53, v163, -1, s[48:49]
	v_cmp_lt_u32_e64 s[34:35], s20, v54
	v_cmp_eq_u32_e64 s[36:37], s20, v54
	v_cmp_lt_u32_e64 s[48:49], s20, v55
	v_cmp_eq_u32_e64 s[50:51], s20, v55
	v_subrev_u32_e32 v162, 0x502, v169
	v_subrev_u32_e32 v163, 0x503, v169
	v_cndmask_b32_e64 v162, 0, v162, s[36:37]
	v_cndmask_b32_e64 v163, 0, v163, s[50:51]
	v_cndmask_b32_e64 v54, v162, -1, s[34:35]
	v_cndmask_b32_e64 v55, v163, -1, s[48:49]
	s_cmp_le_u32 s23, 6
	s_cbranch_scc1 .Ltk0_binit
	v_cmp_lt_u32_e64 s[34:35], s20, v56
	v_cmp_eq_u32_e64 s[36:37], s20, v56
	v_cmp_lt_u32_e64 s[48:49], s20, v57
	v_cmp_eq_u32_e64 s[50:51], s20, v57
	v_subrev_u32_e32 v162, 0x600, v169
	v_subrev_u32_e32 v163, 0x601, v169
	v_cndmask_b32_e64 v162, 0, v162, s[36:37]
	v_cndmask_b32_e64 v163, 0, v163, s[50:51]
	v_cndmask_b32_e64 v56, v162, -1, s[34:35]
	v_cndmask_b32_e64 v57, v163, -1, s[48:49]
	v_cmp_lt_u32_e64 s[34:35], s20, v58
	v_cmp_eq_u32_e64 s[36:37], s20, v58
	v_cmp_lt_u32_e64 s[48:49], s20, v59
	v_cmp_eq_u32_e64 s[50:51], s20, v59
	v_subrev_u32_e32 v162, 0x602, v169
	v_subrev_u32_e32 v163, 0x603, v169
	v_cndmask_b32_e64 v162, 0, v162, s[36:37]
	v_cndmask_b32_e64 v163, 0, v163, s[50:51]
	v_cndmask_b32_e64 v58, v162, -1, s[34:35]
	v_cndmask_b32_e64 v59, v163, -1, s[48:49]
	v_cmp_lt_u32_e64 s[34:35], s20, v60
	v_cmp_eq_u32_e64 s[36:37], s20, v60
	v_cmp_lt_u32_e64 s[48:49], s20, v61
	v_cmp_eq_u32_e64 s[50:51], s20, v61
	v_subrev_u32_e32 v162, 0x700, v169
	v_subrev_u32_e32 v163, 0x701, v169
	v_cndmask_b32_e64 v162, 0, v162, s[36:37]
	v_cndmask_b32_e64 v163, 0, v163, s[50:51]
	v_cndmask_b32_e64 v60, v162, -1, s[34:35]
	v_cndmask_b32_e64 v61, v163, -1, s[48:49]
	v_cmp_lt_u32_e64 s[34:35], s20, v62
	v_cmp_eq_u32_e64 s[36:37], s20, v62
	v_cmp_lt_u32_e64 s[48:49], s20, v63
	v_cmp_eq_u32_e64 s[50:51], s20, v63
	v_subrev_u32_e32 v162, 0x702, v169
	v_subrev_u32_e32 v163, 0x703, v169
	v_cndmask_b32_e64 v162, 0, v162, s[36:37]
	v_cndmask_b32_e64 v163, 0, v163, s[50:51]
	v_cndmask_b32_e64 v62, v162, -1, s[34:35]
	v_cndmask_b32_e64 v63, v163, -1, s[48:49]
	s_cmp_le_u32 s23, 8
	s_cbranch_scc1 .Ltk0_binit
	v_cmp_lt_u32_e64 s[34:35], s20, v64
	v_cmp_eq_u32_e64 s[36:37], s20, v64
	v_cmp_lt_u32_e64 s[48:49], s20, v65
	v_cmp_eq_u32_e64 s[50:51], s20, v65
	v_subrev_u32_e32 v162, 0x800, v169
	v_subrev_u32_e32 v163, 0x801, v169
	v_cndmask_b32_e64 v162, 0, v162, s[36:37]
	v_cndmask_b32_e64 v163, 0, v163, s[50:51]
	v_cndmask_b32_e64 v64, v162, -1, s[34:35]
	v_cndmask_b32_e64 v65, v163, -1, s[48:49]
	v_cmp_lt_u32_e64 s[34:35], s20, v66
	v_cmp_eq_u32_e64 s[36:37], s20, v66
	v_cmp_lt_u32_e64 s[48:49], s20, v67
	v_cmp_eq_u32_e64 s[50:51], s20, v67
	v_subrev_u32_e32 v162, 0x802, v169
	v_subrev_u32_e32 v163, 0x803, v169
	v_cndmask_b32_e64 v162, 0, v162, s[36:37]
	v_cndmask_b32_e64 v163, 0, v163, s[50:51]
	v_cndmask_b32_e64 v66, v162, -1, s[34:35]
	v_cndmask_b32_e64 v67, v163, -1, s[48:49]
	v_cmp_lt_u32_e64 s[34:35], s20, v68
	v_cmp_eq_u32_e64 s[36:37], s20, v68
	v_cmp_lt_u32_e64 s[48:49], s20, v69
	v_cmp_eq_u32_e64 s[50:51], s20, v69
	v_subrev_u32_e32 v162, 0x900, v169
	v_subrev_u32_e32 v163, 0x901, v169
	v_cndmask_b32_e64 v162, 0, v162, s[36:37]
	v_cndmask_b32_e64 v163, 0, v163, s[50:51]
	v_cndmask_b32_e64 v68, v162, -1, s[34:35]
	v_cndmask_b32_e64 v69, v163, -1, s[48:49]
	v_cmp_lt_u32_e64 s[34:35], s20, v70
	v_cmp_eq_u32_e64 s[36:37], s20, v70
	v_cmp_lt_u32_e64 s[48:49], s20, v71
	v_cmp_eq_u32_e64 s[50:51], s20, v71
	v_subrev_u32_e32 v162, 0x902, v169
	v_subrev_u32_e32 v163, 0x903, v169
	v_cndmask_b32_e64 v162, 0, v162, s[36:37]
	v_cndmask_b32_e64 v163, 0, v163, s[50:51]
	v_cndmask_b32_e64 v70, v162, -1, s[34:35]
	v_cndmask_b32_e64 v71, v163, -1, s[48:49]
	s_cmp_le_u32 s23, 10
	s_cbranch_scc1 .Ltk0_binit
	v_cmp_lt_u32_e64 s[34:35], s20, v72
	v_cmp_eq_u32_e64 s[36:37], s20, v72
	v_cmp_lt_u32_e64 s[48:49], s20, v73
	v_cmp_eq_u32_e64 s[50:51], s20, v73
	v_subrev_u32_e32 v162, 0xa00, v169
	v_subrev_u32_e32 v163, 0xa01, v169
	v_cndmask_b32_e64 v162, 0, v162, s[36:37]
	v_cndmask_b32_e64 v163, 0, v163, s[50:51]
	v_cndmask_b32_e64 v72, v162, -1, s[34:35]
	v_cndmask_b32_e64 v73, v163, -1, s[48:49]
	v_cmp_lt_u32_e64 s[34:35], s20, v74
	v_cmp_eq_u32_e64 s[36:37], s20, v74
	v_cmp_lt_u32_e64 s[48:49], s20, v75
	v_cmp_eq_u32_e64 s[50:51], s20, v75
	v_subrev_u32_e32 v162, 0xa02, v169
	v_subrev_u32_e32 v163, 0xa03, v169
	v_cndmask_b32_e64 v162, 0, v162, s[36:37]
	v_cndmask_b32_e64 v163, 0, v163, s[50:51]
	v_cndmask_b32_e64 v74, v162, -1, s[34:35]
	v_cndmask_b32_e64 v75, v163, -1, s[48:49]
	v_cmp_lt_u32_e64 s[34:35], s20, v76
	v_cmp_eq_u32_e64 s[36:37], s20, v76
	v_cmp_lt_u32_e64 s[48:49], s20, v77
	v_cmp_eq_u32_e64 s[50:51], s20, v77
	v_subrev_u32_e32 v162, 0xb00, v169
	v_subrev_u32_e32 v163, 0xb01, v169
	v_cndmask_b32_e64 v162, 0, v162, s[36:37]
	v_cndmask_b32_e64 v163, 0, v163, s[50:51]
	v_cndmask_b32_e64 v76, v162, -1, s[34:35]
	v_cndmask_b32_e64 v77, v163, -1, s[48:49]
	v_cmp_lt_u32_e64 s[34:35], s20, v78
	v_cmp_eq_u32_e64 s[36:37], s20, v78
	v_cmp_lt_u32_e64 s[48:49], s20, v79
	v_cmp_eq_u32_e64 s[50:51], s20, v79
	v_subrev_u32_e32 v162, 0xb02, v169
	v_subrev_u32_e32 v163, 0xb03, v169
	v_cndmask_b32_e64 v162, 0, v162, s[36:37]
	v_cndmask_b32_e64 v163, 0, v163, s[50:51]
	v_cndmask_b32_e64 v78, v162, -1, s[34:35]
	v_cndmask_b32_e64 v79, v163, -1, s[48:49]
	s_cmp_le_u32 s23, 12
	s_cbranch_scc1 .Ltk0_binit
	v_cmp_lt_u32_e64 s[34:35], s20, v80
	v_cmp_eq_u32_e64 s[36:37], s20, v80
	v_cmp_lt_u32_e64 s[48:49], s20, v81
	v_cmp_eq_u32_e64 s[50:51], s20, v81
	v_subrev_u32_e32 v162, 0xc00, v169
	v_subrev_u32_e32 v163, 0xc01, v169
	v_cndmask_b32_e64 v162, 0, v162, s[36:37]
	v_cndmask_b32_e64 v163, 0, v163, s[50:51]
	v_cndmask_b32_e64 v80, v162, -1, s[34:35]
	v_cndmask_b32_e64 v81, v163, -1, s[48:49]
	v_cmp_lt_u32_e64 s[34:35], s20, v82
	v_cmp_eq_u32_e64 s[36:37], s20, v82
	v_cmp_lt_u32_e64 s[48:49], s20, v83
	v_cmp_eq_u32_e64 s[50:51], s20, v83
	v_subrev_u32_e32 v162, 0xc02, v169
	v_subrev_u32_e32 v163, 0xc03, v169
	v_cndmask_b32_e64 v162, 0, v162, s[36:37]
	v_cndmask_b32_e64 v163, 0, v163, s[50:51]
	v_cndmask_b32_e64 v82, v162, -1, s[34:35]
	v_cndmask_b32_e64 v83, v163, -1, s[48:49]
	v_cmp_lt_u32_e64 s[34:35], s20, v84
	v_cmp_eq_u32_e64 s[36:37], s20, v84
	v_cmp_lt_u32_e64 s[48:49], s20, v85
	v_cmp_eq_u32_e64 s[50:51], s20, v85
	v_subrev_u32_e32 v162, 0xd00, v169
	v_subrev_u32_e32 v163, 0xd01, v169
	v_cndmask_b32_e64 v162, 0, v162, s[36:37]
	v_cndmask_b32_e64 v163, 0, v163, s[50:51]
	v_cndmask_b32_e64 v84, v162, -1, s[34:35]
	v_cndmask_b32_e64 v85, v163, -1, s[48:49]
	v_cmp_lt_u32_e64 s[34:35], s20, v86
	v_cmp_eq_u32_e64 s[36:37], s20, v86
	v_cmp_lt_u32_e64 s[48:49], s20, v87
	v_cmp_eq_u32_e64 s[50:51], s20, v87
	v_subrev_u32_e32 v162, 0xd02, v169
	v_subrev_u32_e32 v163, 0xd03, v169
	v_cndmask_b32_e64 v162, 0, v162, s[36:37]
	v_cndmask_b32_e64 v163, 0, v163, s[50:51]
	v_cndmask_b32_e64 v86, v162, -1, s[34:35]
	v_cndmask_b32_e64 v87, v163, -1, s[48:49]
	s_cmp_le_u32 s23, 14
	s_cbranch_scc1 .Ltk0_binit
	v_cmp_lt_u32_e64 s[34:35], s20, v88
	v_cmp_eq_u32_e64 s[36:37], s20, v88
	v_cmp_lt_u32_e64 s[48:49], s20, v89
	v_cmp_eq_u32_e64 s[50:51], s20, v89
	v_subrev_u32_e32 v162, 0xe00, v169
	v_subrev_u32_e32 v163, 0xe01, v169
	v_cndmask_b32_e64 v162, 0, v162, s[36:37]
	v_cndmask_b32_e64 v163, 0, v163, s[50:51]
	v_cndmask_b32_e64 v88, v162, -1, s[34:35]
	v_cndmask_b32_e64 v89, v163, -1, s[48:49]
	v_cmp_lt_u32_e64 s[34:35], s20, v90
	v_cmp_eq_u32_e64 s[36:37], s20, v90
	v_cmp_lt_u32_e64 s[48:49], s20, v91
	v_cmp_eq_u32_e64 s[50:51], s20, v91
	v_subrev_u32_e32 v162, 0xe02, v169
	v_subrev_u32_e32 v163, 0xe03, v169
	v_cndmask_b32_e64 v162, 0, v162, s[36:37]
	v_cndmask_b32_e64 v163, 0, v163, s[50:51]
	v_cndmask_b32_e64 v90, v162, -1, s[34:35]
	v_cndmask_b32_e64 v91, v163, -1, s[48:49]
	v_cmp_lt_u32_e64 s[34:35], s20, v92
	v_cmp_eq_u32_e64 s[36:37], s20, v92
	v_cmp_lt_u32_e64 s[48:49], s20, v93
	v_cmp_eq_u32_e64 s[50:51], s20, v93
	v_subrev_u32_e32 v162, 0xf00, v169
	v_subrev_u32_e32 v163, 0xf01, v169
	v_cndmask_b32_e64 v162, 0, v162, s[36:37]
	v_cndmask_b32_e64 v163, 0, v163, s[50:51]
	v_cndmask_b32_e64 v92, v162, -1, s[34:35]
	v_cndmask_b32_e64 v93, v163, -1, s[48:49]
	v_cmp_lt_u32_e64 s[34:35], s20, v94
	v_cmp_eq_u32_e64 s[36:37], s20, v94
	v_cmp_lt_u32_e64 s[48:49], s20, v95
	v_cmp_eq_u32_e64 s[50:51], s20, v95
	v_subrev_u32_e32 v162, 0xf02, v169
	v_subrev_u32_e32 v163, 0xf03, v169
	v_cndmask_b32_e64 v162, 0, v162, s[36:37]
	v_cndmask_b32_e64 v163, 0, v163, s[50:51]
	v_cndmask_b32_e64 v94, v162, -1, s[34:35]
	v_cndmask_b32_e64 v95, v163, -1, s[48:49]
	s_cmp_le_u32 s23, 16
	s_cbranch_scc1 .Ltk0_binit
	v_cmp_lt_u32_e64 s[34:35], s20, v96
	v_cmp_eq_u32_e64 s[36:37], s20, v96
	v_cmp_lt_u32_e64 s[48:49], s20, v97
	v_cmp_eq_u32_e64 s[50:51], s20, v97
	v_subrev_u32_e32 v162, 0x1000, v169
	v_subrev_u32_e32 v163, 0x1001, v169
	v_cndmask_b32_e64 v162, 0, v162, s[36:37]
	v_cndmask_b32_e64 v163, 0, v163, s[50:51]
	v_cndmask_b32_e64 v96, v162, -1, s[34:35]
	v_cndmask_b32_e64 v97, v163, -1, s[48:49]
	v_cmp_lt_u32_e64 s[34:35], s20, v98
	v_cmp_eq_u32_e64 s[36:37], s20, v98
	v_cmp_lt_u32_e64 s[48:49], s20, v99
	v_cmp_eq_u32_e64 s[50:51], s20, v99
	v_subrev_u32_e32 v162, 0x1002, v169
	v_subrev_u32_e32 v163, 0x1003, v169
	v_cndmask_b32_e64 v162, 0, v162, s[36:37]
	v_cndmask_b32_e64 v163, 0, v163, s[50:51]
	v_cndmask_b32_e64 v98, v162, -1, s[34:35]
	v_cndmask_b32_e64 v99, v163, -1, s[48:49]
	v_cmp_lt_u32_e64 s[34:35], s20, v100
	v_cmp_eq_u32_e64 s[36:37], s20, v100
	v_cmp_lt_u32_e64 s[48:49], s20, v101
	v_cmp_eq_u32_e64 s[50:51], s20, v101
	v_subrev_u32_e32 v162, 0x1100, v169
	v_subrev_u32_e32 v163, 0x1101, v169
	v_cndmask_b32_e64 v162, 0, v162, s[36:37]
	v_cndmask_b32_e64 v163, 0, v163, s[50:51]
	v_cndmask_b32_e64 v100, v162, -1, s[34:35]
	v_cndmask_b32_e64 v101, v163, -1, s[48:49]
	v_cmp_lt_u32_e64 s[34:35], s20, v102
	v_cmp_eq_u32_e64 s[36:37], s20, v102
	v_cmp_lt_u32_e64 s[48:49], s20, v103
	v_cmp_eq_u32_e64 s[50:51], s20, v103
	v_subrev_u32_e32 v162, 0x1102, v169
	v_subrev_u32_e32 v163, 0x1103, v169
	v_cndmask_b32_e64 v162, 0, v162, s[36:37]
	v_cndmask_b32_e64 v163, 0, v163, s[50:51]
	v_cndmask_b32_e64 v102, v162, -1, s[34:35]
	v_cndmask_b32_e64 v103, v163, -1, s[48:49]
	s_cmp_le_u32 s23, 18
	s_cbranch_scc1 .Ltk0_binit
	v_cmp_lt_u32_e64 s[34:35], s20, v104
	v_cmp_eq_u32_e64 s[36:37], s20, v104
	v_cmp_lt_u32_e64 s[48:49], s20, v105
	v_cmp_eq_u32_e64 s[50:51], s20, v105
	v_subrev_u32_e32 v162, 0x1200, v169
	v_subrev_u32_e32 v163, 0x1201, v169
	v_cndmask_b32_e64 v162, 0, v162, s[36:37]
	v_cndmask_b32_e64 v163, 0, v163, s[50:51]
	v_cndmask_b32_e64 v104, v162, -1, s[34:35]
	v_cndmask_b32_e64 v105, v163, -1, s[48:49]
	v_cmp_lt_u32_e64 s[34:35], s20, v106
	v_cmp_eq_u32_e64 s[36:37], s20, v106
	v_cmp_lt_u32_e64 s[48:49], s20, v107
	v_cmp_eq_u32_e64 s[50:51], s20, v107
	v_subrev_u32_e32 v162, 0x1202, v169
	v_subrev_u32_e32 v163, 0x1203, v169
	v_cndmask_b32_e64 v162, 0, v162, s[36:37]
	v_cndmask_b32_e64 v163, 0, v163, s[50:51]
	v_cndmask_b32_e64 v106, v162, -1, s[34:35]
	v_cndmask_b32_e64 v107, v163, -1, s[48:49]
	v_cmp_lt_u32_e64 s[34:35], s20, v108
	v_cmp_eq_u32_e64 s[36:37], s20, v108
	v_cmp_lt_u32_e64 s[48:49], s20, v109
	v_cmp_eq_u32_e64 s[50:51], s20, v109
	v_subrev_u32_e32 v162, 0x1300, v169
	v_subrev_u32_e32 v163, 0x1301, v169
	v_cndmask_b32_e64 v162, 0, v162, s[36:37]
	v_cndmask_b32_e64 v163, 0, v163, s[50:51]
	v_cndmask_b32_e64 v108, v162, -1, s[34:35]
	v_cndmask_b32_e64 v109, v163, -1, s[48:49]
	v_cmp_lt_u32_e64 s[34:35], s20, v110
	v_cmp_eq_u32_e64 s[36:37], s20, v110
	v_cmp_lt_u32_e64 s[48:49], s20, v111
	v_cmp_eq_u32_e64 s[50:51], s20, v111
	v_subrev_u32_e32 v162, 0x1302, v169
	v_subrev_u32_e32 v163, 0x1303, v169
	v_cndmask_b32_e64 v162, 0, v162, s[36:37]
	v_cndmask_b32_e64 v163, 0, v163, s[50:51]
	v_cndmask_b32_e64 v110, v162, -1, s[34:35]
	v_cndmask_b32_e64 v111, v163, -1, s[48:49]
	s_cmp_le_u32 s23, 20
	s_cbranch_scc1 .Ltk0_binit
	v_cmp_lt_u32_e64 s[34:35], s20, v112
	v_cmp_eq_u32_e64 s[36:37], s20, v112
	v_cmp_lt_u32_e64 s[48:49], s20, v113
	v_cmp_eq_u32_e64 s[50:51], s20, v113
	v_subrev_u32_e32 v162, 0x1400, v169
	v_subrev_u32_e32 v163, 0x1401, v169
	v_cndmask_b32_e64 v162, 0, v162, s[36:37]
	v_cndmask_b32_e64 v163, 0, v163, s[50:51]
	v_cndmask_b32_e64 v112, v162, -1, s[34:35]
	v_cndmask_b32_e64 v113, v163, -1, s[48:49]
	v_cmp_lt_u32_e64 s[34:35], s20, v114
	v_cmp_eq_u32_e64 s[36:37], s20, v114
	v_cmp_lt_u32_e64 s[48:49], s20, v115
	v_cmp_eq_u32_e64 s[50:51], s20, v115
	v_subrev_u32_e32 v162, 0x1402, v169
	v_subrev_u32_e32 v163, 0x1403, v169
	v_cndmask_b32_e64 v162, 0, v162, s[36:37]
	v_cndmask_b32_e64 v163, 0, v163, s[50:51]
	v_cndmask_b32_e64 v114, v162, -1, s[34:35]
	v_cndmask_b32_e64 v115, v163, -1, s[48:49]
	v_cmp_lt_u32_e64 s[34:35], s20, v116
	v_cmp_eq_u32_e64 s[36:37], s20, v116
	v_cmp_lt_u32_e64 s[48:49], s20, v117
	v_cmp_eq_u32_e64 s[50:51], s20, v117
	v_subrev_u32_e32 v162, 0x1500, v169
	v_subrev_u32_e32 v163, 0x1501, v169
	v_cndmask_b32_e64 v162, 0, v162, s[36:37]
	v_cndmask_b32_e64 v163, 0, v163, s[50:51]
	v_cndmask_b32_e64 v116, v162, -1, s[34:35]
	v_cndmask_b32_e64 v117, v163, -1, s[48:49]
	v_cmp_lt_u32_e64 s[34:35], s20, v118
	v_cmp_eq_u32_e64 s[36:37], s20, v118
	v_cmp_lt_u32_e64 s[48:49], s20, v119
	v_cmp_eq_u32_e64 s[50:51], s20, v119
	v_subrev_u32_e32 v162, 0x1502, v169
	v_subrev_u32_e32 v163, 0x1503, v169
	v_cndmask_b32_e64 v162, 0, v162, s[36:37]
	v_cndmask_b32_e64 v163, 0, v163, s[50:51]
	v_cndmask_b32_e64 v118, v162, -1, s[34:35]
	v_cndmask_b32_e64 v119, v163, -1, s[48:49]
	s_cmp_le_u32 s23, 22
	s_cbranch_scc1 .Ltk0_binit
	v_cmp_lt_u32_e64 s[34:35], s20, v120
	v_cmp_eq_u32_e64 s[36:37], s20, v120
	v_cmp_lt_u32_e64 s[48:49], s20, v121
	v_cmp_eq_u32_e64 s[50:51], s20, v121
	v_subrev_u32_e32 v162, 0x1600, v169
	v_subrev_u32_e32 v163, 0x1601, v169
	v_cndmask_b32_e64 v162, 0, v162, s[36:37]
	v_cndmask_b32_e64 v163, 0, v163, s[50:51]
	v_cndmask_b32_e64 v120, v162, -1, s[34:35]
	v_cndmask_b32_e64 v121, v163, -1, s[48:49]
	v_cmp_lt_u32_e64 s[34:35], s20, v122
	v_cmp_eq_u32_e64 s[36:37], s20, v122
	v_cmp_lt_u32_e64 s[48:49], s20, v123
	v_cmp_eq_u32_e64 s[50:51], s20, v123
	v_subrev_u32_e32 v162, 0x1602, v169
	v_subrev_u32_e32 v163, 0x1603, v169
	v_cndmask_b32_e64 v162, 0, v162, s[36:37]
	v_cndmask_b32_e64 v163, 0, v163, s[50:51]
	v_cndmask_b32_e64 v122, v162, -1, s[34:35]
	v_cndmask_b32_e64 v123, v163, -1, s[48:49]
	v_cmp_lt_u32_e64 s[34:35], s20, v124
	v_cmp_eq_u32_e64 s[36:37], s20, v124
	v_cmp_lt_u32_e64 s[48:49], s20, v125
	v_cmp_eq_u32_e64 s[50:51], s20, v125
	v_subrev_u32_e32 v162, 0x1700, v169
	v_subrev_u32_e32 v163, 0x1701, v169
	v_cndmask_b32_e64 v162, 0, v162, s[36:37]
	v_cndmask_b32_e64 v163, 0, v163, s[50:51]
	v_cndmask_b32_e64 v124, v162, -1, s[34:35]
	v_cndmask_b32_e64 v125, v163, -1, s[48:49]
	v_cmp_lt_u32_e64 s[34:35], s20, v126
	v_cmp_eq_u32_e64 s[36:37], s20, v126
	v_cmp_lt_u32_e64 s[48:49], s20, v127
	v_cmp_eq_u32_e64 s[50:51], s20, v127
	v_subrev_u32_e32 v162, 0x1702, v169
	v_subrev_u32_e32 v163, 0x1703, v169
	v_cndmask_b32_e64 v162, 0, v162, s[36:37]
	v_cndmask_b32_e64 v163, 0, v163, s[50:51]
	v_cndmask_b32_e64 v126, v162, -1, s[34:35]
	v_cndmask_b32_e64 v127, v163, -1, s[48:49]
	s_cmp_le_u32 s23, 24
	s_cbranch_scc1 .Ltk0_binit
	v_cmp_lt_u32_e64 s[34:35], s20, v128
	v_cmp_eq_u32_e64 s[36:37], s20, v128
	v_cmp_lt_u32_e64 s[48:49], s20, v129
	v_cmp_eq_u32_e64 s[50:51], s20, v129
	v_subrev_u32_e32 v162, 0x1800, v169
	v_subrev_u32_e32 v163, 0x1801, v169
	v_cndmask_b32_e64 v162, 0, v162, s[36:37]
	v_cndmask_b32_e64 v163, 0, v163, s[50:51]
	v_cndmask_b32_e64 v128, v162, -1, s[34:35]
	v_cndmask_b32_e64 v129, v163, -1, s[48:49]
	v_cmp_lt_u32_e64 s[34:35], s20, v130
	v_cmp_eq_u32_e64 s[36:37], s20, v130
	v_cmp_lt_u32_e64 s[48:49], s20, v131
	v_cmp_eq_u32_e64 s[50:51], s20, v131
	v_subrev_u32_e32 v162, 0x1802, v169
	v_subrev_u32_e32 v163, 0x1803, v169
	v_cndmask_b32_e64 v162, 0, v162, s[36:37]
	v_cndmask_b32_e64 v163, 0, v163, s[50:51]
	v_cndmask_b32_e64 v130, v162, -1, s[34:35]
	v_cndmask_b32_e64 v131, v163, -1, s[48:49]
	v_cmp_lt_u32_e64 s[34:35], s20, v132
	v_cmp_eq_u32_e64 s[36:37], s20, v132
	v_cmp_lt_u32_e64 s[48:49], s20, v133
	v_cmp_eq_u32_e64 s[50:51], s20, v133
	v_subrev_u32_e32 v162, 0x1900, v169
	v_subrev_u32_e32 v163, 0x1901, v169
	v_cndmask_b32_e64 v162, 0, v162, s[36:37]
	v_cndmask_b32_e64 v163, 0, v163, s[50:51]
	v_cndmask_b32_e64 v132, v162, -1, s[34:35]
	v_cndmask_b32_e64 v133, v163, -1, s[48:49]
	v_cmp_lt_u32_e64 s[34:35], s20, v134
	v_cmp_eq_u32_e64 s[36:37], s20, v134
	v_cmp_lt_u32_e64 s[48:49], s20, v135
	v_cmp_eq_u32_e64 s[50:51], s20, v135
	v_subrev_u32_e32 v162, 0x1902, v169
	v_subrev_u32_e32 v163, 0x1903, v169
	v_cndmask_b32_e64 v162, 0, v162, s[36:37]
	v_cndmask_b32_e64 v163, 0, v163, s[50:51]
	v_cndmask_b32_e64 v134, v162, -1, s[34:35]
	v_cndmask_b32_e64 v135, v163, -1, s[48:49]
	s_cmp_le_u32 s23, 26
	s_cbranch_scc1 .Ltk0_binit
	v_cmp_lt_u32_e64 s[34:35], s20, v136
	v_cmp_eq_u32_e64 s[36:37], s20, v136
	v_cmp_lt_u32_e64 s[48:49], s20, v137
	v_cmp_eq_u32_e64 s[50:51], s20, v137
	v_subrev_u32_e32 v162, 0x1a00, v169
	v_subrev_u32_e32 v163, 0x1a01, v169
	v_cndmask_b32_e64 v162, 0, v162, s[36:37]
	v_cndmask_b32_e64 v163, 0, v163, s[50:51]
	v_cndmask_b32_e64 v136, v162, -1, s[34:35]
	v_cndmask_b32_e64 v137, v163, -1, s[48:49]
	v_cmp_lt_u32_e64 s[34:35], s20, v138
	v_cmp_eq_u32_e64 s[36:37], s20, v138
	v_cmp_lt_u32_e64 s[48:49], s20, v139
	v_cmp_eq_u32_e64 s[50:51], s20, v139
	v_subrev_u32_e32 v162, 0x1a02, v169
	v_subrev_u32_e32 v163, 0x1a03, v169
	v_cndmask_b32_e64 v162, 0, v162, s[36:37]
	v_cndmask_b32_e64 v163, 0, v163, s[50:51]
	v_cndmask_b32_e64 v138, v162, -1, s[34:35]
	v_cndmask_b32_e64 v139, v163, -1, s[48:49]
	v_cmp_lt_u32_e64 s[34:35], s20, v140
	v_cmp_eq_u32_e64 s[36:37], s20, v140
	v_cmp_lt_u32_e64 s[48:49], s20, v141
	v_cmp_eq_u32_e64 s[50:51], s20, v141
	v_subrev_u32_e32 v162, 0x1b00, v169
	v_subrev_u32_e32 v163, 0x1b01, v169
	v_cndmask_b32_e64 v162, 0, v162, s[36:37]
	v_cndmask_b32_e64 v163, 0, v163, s[50:51]
	v_cndmask_b32_e64 v140, v162, -1, s[34:35]
	v_cndmask_b32_e64 v141, v163, -1, s[48:49]
	v_cmp_lt_u32_e64 s[34:35], s20, v142
	v_cmp_eq_u32_e64 s[36:37], s20, v142
	v_cmp_lt_u32_e64 s[48:49], s20, v143
	v_cmp_eq_u32_e64 s[50:51], s20, v143
	v_subrev_u32_e32 v162, 0x1b02, v169
	v_subrev_u32_e32 v163, 0x1b03, v169
	v_cndmask_b32_e64 v162, 0, v162, s[36:37]
	v_cndmask_b32_e64 v163, 0, v163, s[50:51]
	v_cndmask_b32_e64 v142, v162, -1, s[34:35]
	v_cndmask_b32_e64 v143, v163, -1, s[48:49]
	s_cmp_le_u32 s23, 28
	s_cbranch_scc1 .Ltk0_binit
	v_cmp_lt_u32_e64 s[34:35], s20, v144
	v_cmp_eq_u32_e64 s[36:37], s20, v144
	v_cmp_lt_u32_e64 s[48:49], s20, v145
	v_cmp_eq_u32_e64 s[50:51], s20, v145
	v_subrev_u32_e32 v162, 0x1c00, v169
	v_subrev_u32_e32 v163, 0x1c01, v169
	v_cndmask_b32_e64 v162, 0, v162, s[36:37]
	v_cndmask_b32_e64 v163, 0, v163, s[50:51]
	v_cndmask_b32_e64 v144, v162, -1, s[34:35]
	v_cndmask_b32_e64 v145, v163, -1, s[48:49]
	v_cmp_lt_u32_e64 s[34:35], s20, v146
	v_cmp_eq_u32_e64 s[36:37], s20, v146
	v_cmp_lt_u32_e64 s[48:49], s20, v147
	v_cmp_eq_u32_e64 s[50:51], s20, v147
	v_subrev_u32_e32 v162, 0x1c02, v169
	v_subrev_u32_e32 v163, 0x1c03, v169
	v_cndmask_b32_e64 v162, 0, v162, s[36:37]
	v_cndmask_b32_e64 v163, 0, v163, s[50:51]
	v_cndmask_b32_e64 v146, v162, -1, s[34:35]
	v_cndmask_b32_e64 v147, v163, -1, s[48:49]
	v_cmp_lt_u32_e64 s[34:35], s20, v148
	v_cmp_eq_u32_e64 s[36:37], s20, v148
	v_cmp_lt_u32_e64 s[48:49], s20, v149
	v_cmp_eq_u32_e64 s[50:51], s20, v149
	v_subrev_u32_e32 v162, 0x1d00, v169
	v_subrev_u32_e32 v163, 0x1d01, v169
	v_cndmask_b32_e64 v162, 0, v162, s[36:37]
	v_cndmask_b32_e64 v163, 0, v163, s[50:51]
	v_cndmask_b32_e64 v148, v162, -1, s[34:35]
	v_cndmask_b32_e64 v149, v163, -1, s[48:49]
	v_cmp_lt_u32_e64 s[34:35], s20, v150
	v_cmp_eq_u32_e64 s[36:37], s20, v150
	v_cmp_lt_u32_e64 s[48:49], s20, v151
	v_cmp_eq_u32_e64 s[50:51], s20, v151
	v_subrev_u32_e32 v162, 0x1d02, v169
	v_subrev_u32_e32 v163, 0x1d03, v169
	v_cndmask_b32_e64 v162, 0, v162, s[36:37]
	v_cndmask_b32_e64 v163, 0, v163, s[50:51]
	v_cndmask_b32_e64 v150, v162, -1, s[34:35]
	v_cndmask_b32_e64 v151, v163, -1, s[48:49]
	s_cmp_le_u32 s23, 30
	s_cbranch_scc1 .Ltk0_binit
	v_cmp_lt_u32_e64 s[34:35], s20, v152
	v_cmp_eq_u32_e64 s[36:37], s20, v152
	v_cmp_lt_u32_e64 s[48:49], s20, v153
	v_cmp_eq_u32_e64 s[50:51], s20, v153
	v_subrev_u32_e32 v162, 0x1e00, v169
	v_subrev_u32_e32 v163, 0x1e01, v169
	v_cndmask_b32_e64 v162, 0, v162, s[36:37]
	v_cndmask_b32_e64 v163, 0, v163, s[50:51]
	v_cndmask_b32_e64 v152, v162, -1, s[34:35]
	v_cndmask_b32_e64 v153, v163, -1, s[48:49]
	v_cmp_lt_u32_e64 s[34:35], s20, v154
	v_cmp_eq_u32_e64 s[36:37], s20, v154
	v_cmp_lt_u32_e64 s[48:49], s20, v155
	v_cmp_eq_u32_e64 s[50:51], s20, v155
	v_subrev_u32_e32 v162, 0x1e02, v169
	v_subrev_u32_e32 v163, 0x1e03, v169
	v_cndmask_b32_e64 v162, 0, v162, s[36:37]
	v_cndmask_b32_e64 v163, 0, v163, s[50:51]
	v_cndmask_b32_e64 v154, v162, -1, s[34:35]
	v_cndmask_b32_e64 v155, v163, -1, s[48:49]
	v_cmp_lt_u32_e64 s[34:35], s20, v156
	v_cmp_eq_u32_e64 s[36:37], s20, v156
	v_cmp_lt_u32_e64 s[48:49], s20, v157
	v_cmp_eq_u32_e64 s[50:51], s20, v157
	v_subrev_u32_e32 v162, 0x1f00, v169
	v_subrev_u32_e32 v163, 0x1f01, v169
	v_cndmask_b32_e64 v162, 0, v162, s[36:37]
	v_cndmask_b32_e64 v163, 0, v163, s[50:51]
	v_cndmask_b32_e64 v156, v162, -1, s[34:35]
	v_cndmask_b32_e64 v157, v163, -1, s[48:49]
	v_cmp_lt_u32_e64 s[34:35], s20, v158
	v_cmp_eq_u32_e64 s[36:37], s20, v158
	v_cmp_lt_u32_e64 s[48:49], s20, v159
	v_cmp_eq_u32_e64 s[50:51], s20, v159
	v_subrev_u32_e32 v162, 0x1f02, v169
	v_subrev_u32_e32 v163, 0x1f03, v169
	v_cndmask_b32_e64 v162, 0, v162, s[36:37]
	v_cndmask_b32_e64 v163, 0, v163, s[50:51]
	v_cndmask_b32_e64 v158, v162, -1, s[34:35]
	v_cndmask_b32_e64 v159, v163, -1, s[48:49]
	s_branch .Ltk0_binit
.Ltk0_epre:
	s_mov_b32 s30, s20
.Ltk0_emit:
	v_cmp_le_u32_e64 s[34:35], s30, v35
	v_cmp_le_u32_e64 s[36:37], s30, v39
	v_cmp_le_u32_e64 s[48:49], s30, v34
	v_cmp_le_u32_e64 s[50:51], s30, v38
	v_addc_co_u32_e64 v171, vcc, v1, v1, s[34:35]
	v_addc_co_u32_e64 v172, vcc, v1, v1, s[36:37]
	v_cmp_le_u32_e64 s[34:35], s30, v33
	v_cmp_le_u32_e64 s[36:37], s30, v37
	v_addc_co_u32_e64 v171, vcc, v171, v171, s[48:49]
	v_addc_co_u32_e64 v172, vcc, v172, v172, s[50:51]
	v_cmp_le_u32_e64 s[48:49], s30, v32
	v_cmp_le_u32_e64 s[50:51], s30, v36
	v_addc_co_u32_e64 v171, vcc, v171, v171, s[34:35]
	v_addc_co_u32_e64 v172, vcc, v172, v172, s[36:37]
	s_nop 0
	v_addc_co_u32_e64 v171, vcc, v171, v171, s[48:49]
	v_addc_co_u32_e64 v172, vcc, v172, v172, s[50:51]
	v_lshlrev_b32_e32 v171, v167, v171
	v_lshlrev_b32_e32 v172, v167, v172
	s_nop 0
	v_or_b32_dpp v171, v171, v171 quad_perm:[1,0,3,2] row_mask:0xf bank_mask:0xf
	v_or_b32_dpp v172, v172, v172 quad_perm:[1,0,3,2] row_mask:0xf bank_mask:0xf
	s_nop 0
	v_or_b32_dpp v171, v171, v171 quad_perm:[2,3,0,1] row_mask:0xf bank_mask:0xf
	v_or_b32_dpp v172, v172, v172 quad_perm:[2,3,0,1] row_mask:0xf bank_mask:0xf
	s_nop 0
	v_or_b32_dpp v171, v171, v171 row_half_mirror row_mask:0xf bank_mask:0xf
	v_or_b32_dpp v172, v172, v172 row_half_mirror row_mask:0xf bank_mask:0xf
	s_mov_b64 exec, s[80:81]
	global_store_dword v168, v171, s[24:25] offset:0 sc1
	global_store_dword v168, v172, s[24:25] offset:32 sc1
	s_mov_b64 exec, -1
	s_cmp_le_u32 s23, 2
	s_cbranch_scc1 .Ltk0_zf
	v_cmp_le_u32_e64 s[34:35], s30, v43
	v_cmp_le_u32_e64 s[36:37], s30, v47
	v_cmp_le_u32_e64 s[48:49], s30, v42
	v_cmp_le_u32_e64 s[50:51], s30, v46
	v_addc_co_u32_e64 v171, vcc, v1, v1, s[34:35]
	v_addc_co_u32_e64 v172, vcc, v1, v1, s[36:37]
	v_cmp_le_u32_e64 s[34:35], s30, v41
	v_cmp_le_u32_e64 s[36:37], s30, v45
	v_addc_co_u32_e64 v171, vcc, v171, v171, s[48:49]
	v_addc_co_u32_e64 v172, vcc, v172, v172, s[50:51]
	v_cmp_le_u32_e64 s[48:49], s30, v40
	v_cmp_le_u32_e64 s[50:51], s30, v44
	v_addc_co_u32_e64 v171, vcc, v171, v171, s[34:35]
	v_addc_co_u32_e64 v172, vcc, v172, v172, s[36:37]
	s_nop 0
	v_addc_co_u32_e64 v171, vcc, v171, v171, s[48:49]
	v_addc_co_u32_e64 v172, vcc, v172, v172, s[50:51]
	v_lshlrev_b32_e32 v171, v167, v171
	v_lshlrev_b32_e32 v172, v167, v172
	s_nop 0
	v_or_b32_dpp v171, v171, v171 quad_perm:[1,0,3,2] row_mask:0xf bank_mask:0xf
	v_or_b32_dpp v172, v172, v172 quad_perm:[1,0,3,2] row_mask:0xf bank_mask:0xf
	s_nop 0
	v_or_b32_dpp v171, v171, v171 quad_perm:[2,3,0,1] row_mask:0xf bank_mask:0xf
	v_or_b32_dpp v172, v172, v172 quad_perm:[2,3,0,1] row_mask:0xf bank_mask:0xf
	s_nop 0
	v_or_b32_dpp v171, v171, v171 row_half_mirror row_mask:0xf bank_mask:0xf
	v_or_b32_dpp v172, v172, v172 row_half_mirror row_mask:0xf bank_mask:0xf
	s_mov_b64 exec, s[80:81]
	global_store_dword v168, v171, s[24:25] offset:64 sc1
	global_store_dword v168, v172, s[24:25] offset:96 sc1
	s_mov_b64 exec, -1
	s_cmp_le_u32 s23, 4
	s_cbranch_scc1 .Ltk0_zf
	v_cmp_le_u32_e64 s[34:35], s30, v51
	v_cmp_le_u32_e64 s[36:37], s30, v55
	v_cmp_le_u32_e64 s[48:49], s30, v50
	v_cmp_le_u32_e64 s[50:51], s30, v54
	v_addc_co_u32_e64 v171, vcc, v1, v1, s[34:35]
	v_addc_co_u32_e64 v172, vcc, v1, v1, s[36:37]
	v_cmp_le_u32_e64 s[34:35], s30, v49
	v_cmp_le_u32_e64 s[36:37], s30, v53
	v_addc_co_u32_e64 v171, vcc, v171, v171, s[48:49]
	v_addc_co_u32_e64 v172, vcc, v172, v172, s[50:51]
	v_cmp_le_u32_e64 s[48:49], s30, v48
	v_cmp_le_u32_e64 s[50:51], s30, v52
	v_addc_co_u32_e64 v171, vcc, v171, v171, s[34:35]
	v_addc_co_u32_e64 v172, vcc, v172, v172, s[36:37]
	s_nop 0
	v_addc_co_u32_e64 v171, vcc, v171, v171, s[48:49]
	v_addc_co_u32_e64 v172, vcc, v172, v172, s[50:51]
	v_lshlrev_b32_e32 v171, v167, v171
	v_lshlrev_b32_e32 v172, v167, v172
	s_nop 0
	v_or_b32_dpp v171, v171, v171 quad_perm:[1,0,3,2] row_mask:0xf bank_mask:0xf
	v_or_b32_dpp v172, v172, v172 quad_perm:[1,0,3,2] row_mask:0xf bank_mask:0xf
	s_nop 0
	v_or_b32_dpp v171, v171, v171 quad_perm:[2,3,0,1] row_mask:0xf bank_mask:0xf
	v_or_b32_dpp v172, v172, v172 quad_perm:[2,3,0,1] row_mask:0xf bank_mask:0xf
	s_nop 0
	v_or_b32_dpp v171, v171, v171 row_half_mirror row_mask:0xf bank_mask:0xf
	v_or_b32_dpp v172, v172, v172 row_half_mirror row_mask:0xf bank_mask:0xf
	s_mov_b64 exec, s[80:81]
	global_store_dword v168, v171, s[24:25] offset:128 sc1
	global_store_dword v168, v172, s[24:25] offset:160 sc1
	s_mov_b64 exec, -1
	s_cmp_le_u32 s23, 6
	s_cbranch_scc1 .Ltk0_zf
	v_cmp_le_u32_e64 s[34:35], s30, v59
	v_cmp_le_u32_e64 s[36:37], s30, v63
	v_cmp_le_u32_e64 s[48:49], s30, v58
	v_cmp_le_u32_e64 s[50:51], s30, v62
	v_addc_co_u32_e64 v171, vcc, v1, v1, s[34:35]
	v_addc_co_u32_e64 v172, vcc, v1, v1, s[36:37]
	v_cmp_le_u32_e64 s[34:35], s30, v57
	v_cmp_le_u32_e64 s[36:37], s30, v61
	v_addc_co_u32_e64 v171, vcc, v171, v171, s[48:49]
	v_addc_co_u32_e64 v172, vcc, v172, v172, s[50:51]
	v_cmp_le_u32_e64 s[48:49], s30, v56
	v_cmp_le_u32_e64 s[50:51], s30, v60
	v_addc_co_u32_e64 v171, vcc, v171, v171, s[34:35]
	v_addc_co_u32_e64 v172, vcc, v172, v172, s[36:37]
	s_nop 0
	v_addc_co_u32_e64 v171, vcc, v171, v171, s[48:49]
	v_addc_co_u32_e64 v172, vcc, v172, v172, s[50:51]
	v_lshlrev_b32_e32 v171, v167, v171
	v_lshlrev_b32_e32 v172, v167, v172
	s_nop 0
	v_or_b32_dpp v171, v171, v171 quad_perm:[1,0,3,2] row_mask:0xf bank_mask:0xf
	v_or_b32_dpp v172, v172, v172 quad_perm:[1,0,3,2] row_mask:0xf bank_mask:0xf
	s_nop 0
	v_or_b32_dpp v171, v171, v171 quad_perm:[2,3,0,1] row_mask:0xf bank_mask:0xf
	v_or_b32_dpp v172, v172, v172 quad_perm:[2,3,0,1] row_mask:0xf bank_mask:0xf
	s_nop 0
	v_or_b32_dpp v171, v171, v171 row_half_mirror row_mask:0xf bank_mask:0xf
	v_or_b32_dpp v172, v172, v172 row_half_mirror row_mask:0xf bank_mask:0xf
	s_mov_b64 exec, s[80:81]
	global_store_dword v168, v171, s[24:25] offset:192 sc1
	global_store_dword v168, v172, s[24:25] offset:224 sc1
	s_mov_b64 exec, -1
	s_cmp_le_u32 s23, 8
	s_cbranch_scc1 .Ltk0_zf
	v_cmp_le_u32_e64 s[34:35], s30, v67
	v_cmp_le_u32_e64 s[36:37], s30, v71
	v_cmp_le_u32_e64 s[48:49], s30, v66
	v_cmp_le_u32_e64 s[50:51], s30, v70
	v_addc_co_u32_e64 v171, vcc, v1, v1, s[34:35]
	v_addc_co_u32_e64 v172, vcc, v1, v1, s[36:37]
	v_cmp_le_u32_e64 s[34:35], s30, v65
	v_cmp_le_u32_e64 s[36:37], s30, v69
	v_addc_co_u32_e64 v171, vcc, v171, v171, s[48:49]
	v_addc_co_u32_e64 v172, vcc, v172, v172, s[50:51]
	v_cmp_le_u32_e64 s[48:49], s30, v64
	v_cmp_le_u32_e64 s[50:51], s30, v68
	v_addc_co_u32_e64 v171, vcc, v171, v171, s[34:35]
	v_addc_co_u32_e64 v172, vcc, v172, v172, s[36:37]
	s_nop 0
	v_addc_co_u32_e64 v171, vcc, v171, v171, s[48:49]
	v_addc_co_u32_e64 v172, vcc, v172, v172, s[50:51]
	v_lshlrev_b32_e32 v171, v167, v171
	v_lshlrev_b32_e32 v172, v167, v172
	s_nop 0
	v_or_b32_dpp v171, v171, v171 quad_perm:[1,0,3,2] row_mask:0xf bank_mask:0xf
	v_or_b32_dpp v172, v172, v172 quad_perm:[1,0,3,2] row_mask:0xf bank_mask:0xf
	s_nop 0
	v_or_b32_dpp v171, v171, v171 quad_perm:[2,3,0,1] row_mask:0xf bank_mask:0xf
	v_or_b32_dpp v172, v172, v172 quad_perm:[2,3,0,1] row_mask:0xf bank_mask:0xf
	s_nop 0
	v_or_b32_dpp v171, v171, v171 row_half_mirror row_mask:0xf bank_mask:0xf
	v_or_b32_dpp v172, v172, v172 row_half_mirror row_mask:0xf bank_mask:0xf
	s_mov_b64 exec, s[80:81]
	global_store_dword v168, v171, s[24:25] offset:256 sc1
	global_store_dword v168, v172, s[24:25] offset:288 sc1
	s_mov_b64 exec, -1
	s_cmp_le_u32 s23, 10
	s_cbranch_scc1 .Ltk0_zf
	v_cmp_le_u32_e64 s[34:35], s30, v75
	v_cmp_le_u32_e64 s[36:37], s30, v79
	v_cmp_le_u32_e64 s[48:49], s30, v74
	v_cmp_le_u32_e64 s[50:51], s30, v78
	v_addc_co_u32_e64 v171, vcc, v1, v1, s[34:35]
	v_addc_co_u32_e64 v172, vcc, v1, v1, s[36:37]
	v_cmp_le_u32_e64 s[34:35], s30, v73
	v_cmp_le_u32_e64 s[36:37], s30, v77
	v_addc_co_u32_e64 v171, vcc, v171, v171, s[48:49]
	v_addc_co_u32_e64 v172, vcc, v172, v172, s[50:51]
	v_cmp_le_u32_e64 s[48:49], s30, v72
	v_cmp_le_u32_e64 s[50:51], s30, v76
	v_addc_co_u32_e64 v171, vcc, v171, v171, s[34:35]
	v_addc_co_u32_e64 v172, vcc, v172, v172, s[36:37]
	s_nop 0
	v_addc_co_u32_e64 v171, vcc, v171, v171, s[48:49]
	v_addc_co_u32_e64 v172, vcc, v172, v172, s[50:51]
	v_lshlrev_b32_e32 v171, v167, v171
	v_lshlrev_b32_e32 v172, v167, v172
	s_nop 0
	v_or_b32_dpp v171, v171, v171 quad_perm:[1,0,3,2] row_mask:0xf bank_mask:0xf
	v_or_b32_dpp v172, v172, v172 quad_perm:[1,0,3,2] row_mask:0xf bank_mask:0xf
	s_nop 0
	v_or_b32_dpp v171, v171, v171 quad_perm:[2,3,0,1] row_mask:0xf bank_mask:0xf
	v_or_b32_dpp v172, v172, v172 quad_perm:[2,3,0,1] row_mask:0xf bank_mask:0xf
	s_nop 0
	v_or_b32_dpp v171, v171, v171 row_half_mirror row_mask:0xf bank_mask:0xf
	v_or_b32_dpp v172, v172, v172 row_half_mirror row_mask:0xf bank_mask:0xf
	s_mov_b64 exec, s[80:81]
	global_store_dword v168, v171, s[24:25] offset:320 sc1
	global_store_dword v168, v172, s[24:25] offset:352 sc1
	s_mov_b64 exec, -1
	s_cmp_le_u32 s23, 12
	s_cbranch_scc1 .Ltk0_zf
	v_cmp_le_u32_e64 s[34:35], s30, v83
	v_cmp_le_u32_e64 s[36:37], s30, v87
	v_cmp_le_u32_e64 s[48:49], s30, v82
	v_cmp_le_u32_e64 s[50:51], s30, v86
	v_addc_co_u32_e64 v171, vcc, v1, v1, s[34:35]
	v_addc_co_u32_e64 v172, vcc, v1, v1, s[36:37]
	v_cmp_le_u32_e64 s[34:35], s30, v81
	v_cmp_le_u32_e64 s[36:37], s30, v85
	v_addc_co_u32_e64 v171, vcc, v171, v171, s[48:49]
	v_addc_co_u32_e64 v172, vcc, v172, v172, s[50:51]
	v_cmp_le_u32_e64 s[48:49], s30, v80
	v_cmp_le_u32_e64 s[50:51], s30, v84
	v_addc_co_u32_e64 v171, vcc, v171, v171, s[34:35]
	v_addc_co_u32_e64 v172, vcc, v172, v172, s[36:37]
	s_nop 0
	v_addc_co_u32_e64 v171, vcc, v171, v171, s[48:49]
	v_addc_co_u32_e64 v172, vcc, v172, v172, s[50:51]
	v_lshlrev_b32_e32 v171, v167, v171
	v_lshlrev_b32_e32 v172, v167, v172
	s_nop 0
	v_or_b32_dpp v171, v171, v171 quad_perm:[1,0,3,2] row_mask:0xf bank_mask:0xf
	v_or_b32_dpp v172, v172, v172 quad_perm:[1,0,3,2] row_mask:0xf bank_mask:0xf
	s_nop 0
	v_or_b32_dpp v171, v171, v171 quad_perm:[2,3,0,1] row_mask:0xf bank_mask:0xf
	v_or_b32_dpp v172, v172, v172 quad_perm:[2,3,0,1] row_mask:0xf bank_mask:0xf
	s_nop 0
	v_or_b32_dpp v171, v171, v171 row_half_mirror row_mask:0xf bank_mask:0xf
	v_or_b32_dpp v172, v172, v172 row_half_mirror row_mask:0xf bank_mask:0xf
	s_mov_b64 exec, s[80:81]
	global_store_dword v168, v171, s[24:25] offset:384 sc1
	global_store_dword v168, v172, s[24:25] offset:416 sc1
	s_mov_b64 exec, -1
	s_cmp_le_u32 s23, 14
	s_cbranch_scc1 .Ltk0_zf
	v_cmp_le_u32_e64 s[34:35], s30, v91
	v_cmp_le_u32_e64 s[36:37], s30, v95
	v_cmp_le_u32_e64 s[48:49], s30, v90
	v_cmp_le_u32_e64 s[50:51], s30, v94
	v_addc_co_u32_e64 v171, vcc, v1, v1, s[34:35]
	v_addc_co_u32_e64 v172, vcc, v1, v1, s[36:37]
	v_cmp_le_u32_e64 s[34:35], s30, v89
	v_cmp_le_u32_e64 s[36:37], s30, v93
	v_addc_co_u32_e64 v171, vcc, v171, v171, s[48:49]
	v_addc_co_u32_e64 v172, vcc, v172, v172, s[50:51]
	v_cmp_le_u32_e64 s[48:49], s30, v88
	v_cmp_le_u32_e64 s[50:51], s30, v92
	v_addc_co_u32_e64 v171, vcc, v171, v171, s[34:35]
	v_addc_co_u32_e64 v172, vcc, v172, v172, s[36:37]
	s_nop 0
	v_addc_co_u32_e64 v171, vcc, v171, v171, s[48:49]
	v_addc_co_u32_e64 v172, vcc, v172, v172, s[50:51]
	v_lshlrev_b32_e32 v171, v167, v171
	v_lshlrev_b32_e32 v172, v167, v172
	s_nop 0
	v_or_b32_dpp v171, v171, v171 quad_perm:[1,0,3,2] row_mask:0xf bank_mask:0xf
	v_or_b32_dpp v172, v172, v172 quad_perm:[1,0,3,2] row_mask:0xf bank_mask:0xf
	s_nop 0
	v_or_b32_dpp v171, v171, v171 quad_perm:[2,3,0,1] row_mask:0xf bank_mask:0xf
	v_or_b32_dpp v172, v172, v172 quad_perm:[2,3,0,1] row_mask:0xf bank_mask:0xf
	s_nop 0
	v_or_b32_dpp v171, v171, v171 row_half_mirror row_mask:0xf bank_mask:0xf
	v_or_b32_dpp v172, v172, v172 row_half_mirror row_mask:0xf bank_mask:0xf
	s_mov_b64 exec, s[80:81]
	global_store_dword v168, v171, s[24:25] offset:448 sc1
	global_store_dword v168, v172, s[24:25] offset:480 sc1
	s_mov_b64 exec, -1
	s_cmp_le_u32 s23, 16
	s_cbranch_scc1 .Ltk0_zf
	v_cmp_le_u32_e64 s[34:35], s30, v99
	v_cmp_le_u32_e64 s[36:37], s30, v103
	v_cmp_le_u32_e64 s[48:49], s30, v98
	v_cmp_le_u32_e64 s[50:51], s30, v102
	v_addc_co_u32_e64 v171, vcc, v1, v1, s[34:35]
	v_addc_co_u32_e64 v172, vcc, v1, v1, s[36:37]
	v_cmp_le_u32_e64 s[34:35], s30, v97
	v_cmp_le_u32_e64 s[36:37], s30, v101
	v_addc_co_u32_e64 v171, vcc, v171, v171, s[48:49]
	v_addc_co_u32_e64 v172, vcc, v172, v172, s[50:51]
	v_cmp_le_u32_e64 s[48:49], s30, v96
	v_cmp_le_u32_e64 s[50:51], s30, v100
	v_addc_co_u32_e64 v171, vcc, v171, v171, s[34:35]
	v_addc_co_u32_e64 v172, vcc, v172, v172, s[36:37]
	s_nop 0
	v_addc_co_u32_e64 v171, vcc, v171, v171, s[48:49]
	v_addc_co_u32_e64 v172, vcc, v172, v172, s[50:51]
	v_lshlrev_b32_e32 v171, v167, v171
	v_lshlrev_b32_e32 v172, v167, v172
	s_nop 0
	v_or_b32_dpp v171, v171, v171 quad_perm:[1,0,3,2] row_mask:0xf bank_mask:0xf
	v_or_b32_dpp v172, v172, v172 quad_perm:[1,0,3,2] row_mask:0xf bank_mask:0xf
	s_nop 0
	v_or_b32_dpp v171, v171, v171 quad_perm:[2,3,0,1] row_mask:0xf bank_mask:0xf
	v_or_b32_dpp v172, v172, v172 quad_perm:[2,3,0,1] row_mask:0xf bank_mask:0xf
	s_nop 0
	v_or_b32_dpp v171, v171, v171 row_half_mirror row_mask:0xf bank_mask:0xf
	v_or_b32_dpp v172, v172, v172 row_half_mirror row_mask:0xf bank_mask:0xf
	s_mov_b64 exec, s[80:81]
	global_store_dword v168, v171, s[24:25] offset:512 sc1
	global_store_dword v168, v172, s[24:25] offset:544 sc1
	s_mov_b64 exec, -1
	s_cmp_le_u32 s23, 18
	s_cbranch_scc1 .Ltk0_zf
	v_cmp_le_u32_e64 s[34:35], s30, v107
	v_cmp_le_u32_e64 s[36:37], s30, v111
	v_cmp_le_u32_e64 s[48:49], s30, v106
	v_cmp_le_u32_e64 s[50:51], s30, v110
	v_addc_co_u32_e64 v171, vcc, v1, v1, s[34:35]
	v_addc_co_u32_e64 v172, vcc, v1, v1, s[36:37]
	v_cmp_le_u32_e64 s[34:35], s30, v105
	v_cmp_le_u32_e64 s[36:37], s30, v109
	v_addc_co_u32_e64 v171, vcc, v171, v171, s[48:49]
	v_addc_co_u32_e64 v172, vcc, v172, v172, s[50:51]
	v_cmp_le_u32_e64 s[48:49], s30, v104
	v_cmp_le_u32_e64 s[50:51], s30, v108
	v_addc_co_u32_e64 v171, vcc, v171, v171, s[34:35]
	v_addc_co_u32_e64 v172, vcc, v172, v172, s[36:37]
	s_nop 0
	v_addc_co_u32_e64 v171, vcc, v171, v171, s[48:49]
	v_addc_co_u32_e64 v172, vcc, v172, v172, s[50:51]
	v_lshlrev_b32_e32 v171, v167, v171
	v_lshlrev_b32_e32 v172, v167, v172
	s_nop 0
	v_or_b32_dpp v171, v171, v171 quad_perm:[1,0,3,2] row_mask:0xf bank_mask:0xf
	v_or_b32_dpp v172, v172, v172 quad_perm:[1,0,3,2] row_mask:0xf bank_mask:0xf
	s_nop 0
	v_or_b32_dpp v171, v171, v171 quad_perm:[2,3,0,1] row_mask:0xf bank_mask:0xf
	v_or_b32_dpp v172, v172, v172 quad_perm:[2,3,0,1] row_mask:0xf bank_mask:0xf
	s_nop 0
	v_or_b32_dpp v171, v171, v171 row_half_mirror row_mask:0xf bank_mask:0xf
	v_or_b32_dpp v172, v172, v172 row_half_mirror row_mask:0xf bank_mask:0xf
	s_mov_b64 exec, s[80:81]
	global_store_dword v168, v171, s[24:25] offset:576 sc1
	global_store_dword v168, v172, s[24:25] offset:608 sc1
	s_mov_b64 exec, -1
	s_cmp_le_u32 s23, 20
	s_cbranch_scc1 .Ltk0_zf
	v_cmp_le_u32_e64 s[34:35], s30, v115
	v_cmp_le_u32_e64 s[36:37], s30, v119
	v_cmp_le_u32_e64 s[48:49], s30, v114
	v_cmp_le_u32_e64 s[50:51], s30, v118
	v_addc_co_u32_e64 v171, vcc, v1, v1, s[34:35]
	v_addc_co_u32_e64 v172, vcc, v1, v1, s[36:37]
	v_cmp_le_u32_e64 s[34:35], s30, v113
	v_cmp_le_u32_e64 s[36:37], s30, v117
	v_addc_co_u32_e64 v171, vcc, v171, v171, s[48:49]
	v_addc_co_u32_e64 v172, vcc, v172, v172, s[50:51]
	v_cmp_le_u32_e64 s[48:49], s30, v112
	v_cmp_le_u32_e64 s[50:51], s30, v116
	v_addc_co_u32_e64 v171, vcc, v171, v171, s[34:35]
	v_addc_co_u32_e64 v172, vcc, v172, v172, s[36:37]
	s_nop 0
	v_addc_co_u32_e64 v171, vcc, v171, v171, s[48:49]
	v_addc_co_u32_e64 v172, vcc, v172, v172, s[50:51]
	v_lshlrev_b32_e32 v171, v167, v171
	v_lshlrev_b32_e32 v172, v167, v172
	s_nop 0
	v_or_b32_dpp v171, v171, v171 quad_perm:[1,0,3,2] row_mask:0xf bank_mask:0xf
	v_or_b32_dpp v172, v172, v172 quad_perm:[1,0,3,2] row_mask:0xf bank_mask:0xf
	s_nop 0
	v_or_b32_dpp v171, v171, v171 quad_perm:[2,3,0,1] row_mask:0xf bank_mask:0xf
	v_or_b32_dpp v172, v172, v172 quad_perm:[2,3,0,1] row_mask:0xf bank_mask:0xf
	s_nop 0
	v_or_b32_dpp v171, v171, v171 row_half_mirror row_mask:0xf bank_mask:0xf
	v_or_b32_dpp v172, v172, v172 row_half_mirror row_mask:0xf bank_mask:0xf
	s_mov_b64 exec, s[80:81]
	global_store_dword v168, v171, s[24:25] offset:640 sc1
	global_store_dword v168, v172, s[24:25] offset:672 sc1
	s_mov_b64 exec, -1
	s_cmp_le_u32 s23, 22
	s_cbranch_scc1 .Ltk0_zf
	v_cmp_le_u32_e64 s[34:35], s30, v123
	v_cmp_le_u32_e64 s[36:37], s30, v127
	v_cmp_le_u32_e64 s[48:49], s30, v122
	v_cmp_le_u32_e64 s[50:51], s30, v126
	v_addc_co_u32_e64 v171, vcc, v1, v1, s[34:35]
	v_addc_co_u32_e64 v172, vcc, v1, v1, s[36:37]
	v_cmp_le_u32_e64 s[34:35], s30, v121
	v_cmp_le_u32_e64 s[36:37], s30, v125
	v_addc_co_u32_e64 v171, vcc, v171, v171, s[48:49]
	v_addc_co_u32_e64 v172, vcc, v172, v172, s[50:51]
	v_cmp_le_u32_e64 s[48:49], s30, v120
	v_cmp_le_u32_e64 s[50:51], s30, v124
	v_addc_co_u32_e64 v171, vcc, v171, v171, s[34:35]
	v_addc_co_u32_e64 v172, vcc, v172, v172, s[36:37]
	s_nop 0
	v_addc_co_u32_e64 v171, vcc, v171, v171, s[48:49]
	v_addc_co_u32_e64 v172, vcc, v172, v172, s[50:51]
	v_lshlrev_b32_e32 v171, v167, v171
	v_lshlrev_b32_e32 v172, v167, v172
	s_nop 0
	v_or_b32_dpp v171, v171, v171 quad_perm:[1,0,3,2] row_mask:0xf bank_mask:0xf
	v_or_b32_dpp v172, v172, v172 quad_perm:[1,0,3,2] row_mask:0xf bank_mask:0xf
	s_nop 0
	v_or_b32_dpp v171, v171, v171 quad_perm:[2,3,0,1] row_mask:0xf bank_mask:0xf
	v_or_b32_dpp v172, v172, v172 quad_perm:[2,3,0,1] row_mask:0xf bank_mask:0xf
	s_nop 0
	v_or_b32_dpp v171, v171, v171 row_half_mirror row_mask:0xf bank_mask:0xf
	v_or_b32_dpp v172, v172, v172 row_half_mirror row_mask:0xf bank_mask:0xf
	s_mov_b64 exec, s[80:81]
	global_store_dword v168, v171, s[24:25] offset:704 sc1
	global_store_dword v168, v172, s[24:25] offset:736 sc1
	s_mov_b64 exec, -1
	s_cmp_le_u32 s23, 24
	s_cbranch_scc1 .Ltk0_zf
	v_cmp_le_u32_e64 s[34:35], s30, v131
	v_cmp_le_u32_e64 s[36:37], s30, v135
	v_cmp_le_u32_e64 s[48:49], s30, v130
	v_cmp_le_u32_e64 s[50:51], s30, v134
	v_addc_co_u32_e64 v171, vcc, v1, v1, s[34:35]
	v_addc_co_u32_e64 v172, vcc, v1, v1, s[36:37]
	v_cmp_le_u32_e64 s[34:35], s30, v129
	v_cmp_le_u32_e64 s[36:37], s30, v133
	v_addc_co_u32_e64 v171, vcc, v171, v171, s[48:49]
	v_addc_co_u32_e64 v172, vcc, v172, v172, s[50:51]
	v_cmp_le_u32_e64 s[48:49], s30, v128
	v_cmp_le_u32_e64 s[50:51], s30, v132
	v_addc_co_u32_e64 v171, vcc, v171, v171, s[34:35]
	v_addc_co_u32_e64 v172, vcc, v172, v172, s[36:37]
	s_nop 0
	v_addc_co_u32_e64 v171, vcc, v171, v171, s[48:49]
	v_addc_co_u32_e64 v172, vcc, v172, v172, s[50:51]
	v_lshlrev_b32_e32 v171, v167, v171
	v_lshlrev_b32_e32 v172, v167, v172
	s_nop 0
	v_or_b32_dpp v171, v171, v171 quad_perm:[1,0,3,2] row_mask:0xf bank_mask:0xf
	v_or_b32_dpp v172, v172, v172 quad_perm:[1,0,3,2] row_mask:0xf bank_mask:0xf
	s_nop 0
	v_or_b32_dpp v171, v171, v171 quad_perm:[2,3,0,1] row_mask:0xf bank_mask:0xf
	v_or_b32_dpp v172, v172, v172 quad_perm:[2,3,0,1] row_mask:0xf bank_mask:0xf
	s_nop 0
	v_or_b32_dpp v171, v171, v171 row_half_mirror row_mask:0xf bank_mask:0xf
	v_or_b32_dpp v172, v172, v172 row_half_mirror row_mask:0xf bank_mask:0xf
	s_mov_b64 exec, s[80:81]
	global_store_dword v168, v171, s[24:25] offset:768 sc1
	global_store_dword v168, v172, s[24:25] offset:800 sc1
	s_mov_b64 exec, -1
	s_cmp_le_u32 s23, 26
	s_cbranch_scc1 .Ltk0_zf
	v_cmp_le_u32_e64 s[34:35], s30, v139
	v_cmp_le_u32_e64 s[36:37], s30, v143
	v_cmp_le_u32_e64 s[48:49], s30, v138
	v_cmp_le_u32_e64 s[50:51], s30, v142
	v_addc_co_u32_e64 v171, vcc, v1, v1, s[34:35]
	v_addc_co_u32_e64 v172, vcc, v1, v1, s[36:37]
	v_cmp_le_u32_e64 s[34:35], s30, v137
	v_cmp_le_u32_e64 s[36:37], s30, v141
	v_addc_co_u32_e64 v171, vcc, v171, v171, s[48:49]
	v_addc_co_u32_e64 v172, vcc, v172, v172, s[50:51]
	v_cmp_le_u32_e64 s[48:49], s30, v136
	v_cmp_le_u32_e64 s[50:51], s30, v140
	v_addc_co_u32_e64 v171, vcc, v171, v171, s[34:35]
	v_addc_co_u32_e64 v172, vcc, v172, v172, s[36:37]
	s_nop 0
	v_addc_co_u32_e64 v171, vcc, v171, v171, s[48:49]
	v_addc_co_u32_e64 v172, vcc, v172, v172, s[50:51]
	v_lshlrev_b32_e32 v171, v167, v171
	v_lshlrev_b32_e32 v172, v167, v172
	s_nop 0
	v_or_b32_dpp v171, v171, v171 quad_perm:[1,0,3,2] row_mask:0xf bank_mask:0xf
	v_or_b32_dpp v172, v172, v172 quad_perm:[1,0,3,2] row_mask:0xf bank_mask:0xf
	s_nop 0
	v_or_b32_dpp v171, v171, v171 quad_perm:[2,3,0,1] row_mask:0xf bank_mask:0xf
	v_or_b32_dpp v172, v172, v172 quad_perm:[2,3,0,1] row_mask:0xf bank_mask:0xf
	s_nop 0
	v_or_b32_dpp v171, v171, v171 row_half_mirror row_mask:0xf bank_mask:0xf
	v_or_b32_dpp v172, v172, v172 row_half_mirror row_mask:0xf bank_mask:0xf
	s_mov_b64 exec, s[80:81]
	global_store_dword v168, v171, s[24:25] offset:832 sc1
	global_store_dword v168, v172, s[24:25] offset:864 sc1
	s_mov_b64 exec, -1
	s_cmp_le_u32 s23, 28
	s_cbranch_scc1 .Ltk0_zf
	v_cmp_le_u32_e64 s[34:35], s30, v147
	v_cmp_le_u32_e64 s[36:37], s30, v151
	v_cmp_le_u32_e64 s[48:49], s30, v146
	v_cmp_le_u32_e64 s[50:51], s30, v150
	v_addc_co_u32_e64 v171, vcc, v1, v1, s[34:35]
	v_addc_co_u32_e64 v172, vcc, v1, v1, s[36:37]
	v_cmp_le_u32_e64 s[34:35], s30, v145
	v_cmp_le_u32_e64 s[36:37], s30, v149
	v_addc_co_u32_e64 v171, vcc, v171, v171, s[48:49]
	v_addc_co_u32_e64 v172, vcc, v172, v172, s[50:51]
	v_cmp_le_u32_e64 s[48:49], s30, v144
	v_cmp_le_u32_e64 s[50:51], s30, v148
	v_addc_co_u32_e64 v171, vcc, v171, v171, s[34:35]
	v_addc_co_u32_e64 v172, vcc, v172, v172, s[36:37]
	s_nop 0
	v_addc_co_u32_e64 v171, vcc, v171, v171, s[48:49]
	v_addc_co_u32_e64 v172, vcc, v172, v172, s[50:51]
	v_lshlrev_b32_e32 v171, v167, v171
	v_lshlrev_b32_e32 v172, v167, v172
	s_nop 0
	v_or_b32_dpp v171, v171, v171 quad_perm:[1,0,3,2] row_mask:0xf bank_mask:0xf
	v_or_b32_dpp v172, v172, v172 quad_perm:[1,0,3,2] row_mask:0xf bank_mask:0xf
	s_nop 0
	v_or_b32_dpp v171, v171, v171 quad_perm:[2,3,0,1] row_mask:0xf bank_mask:0xf
	v_or_b32_dpp v172, v172, v172 quad_perm:[2,3,0,1] row_mask:0xf bank_mask:0xf
	s_nop 0
	v_or_b32_dpp v171, v171, v171 row_half_mirror row_mask:0xf bank_mask:0xf
	v_or_b32_dpp v172, v172, v172 row_half_mirror row_mask:0xf bank_mask:0xf
	s_mov_b64 exec, s[80:81]
	global_store_dword v168, v171, s[24:25] offset:896 sc1
	global_store_dword v168, v172, s[24:25] offset:928 sc1
	s_mov_b64 exec, -1
	s_cmp_le_u32 s23, 30
	s_cbranch_scc1 .Ltk0_zf
	v_cmp_le_u32_e64 s[34:35], s30, v155
	v_cmp_le_u32_e64 s[36:37], s30, v159
	v_cmp_le_u32_e64 s[48:49], s30, v154
	v_cmp_le_u32_e64 s[50:51], s30, v158
	v_addc_co_u32_e64 v171, vcc, v1, v1, s[34:35]
	v_addc_co_u32_e64 v172, vcc, v1, v1, s[36:37]
	v_cmp_le_u32_e64 s[34:35], s30, v153
	v_cmp_le_u32_e64 s[36:37], s30, v157
	v_addc_co_u32_e64 v171, vcc, v171, v171, s[48:49]
	v_addc_co_u32_e64 v172, vcc, v172, v172, s[50:51]
	v_cmp_le_u32_e64 s[48:49], s30, v152
	v_cmp_le_u32_e64 s[50:51], s30, v156
	v_addc_co_u32_e64 v171, vcc, v171, v171, s[34:35]
	v_addc_co_u32_e64 v172, vcc, v172, v172, s[36:37]
	s_nop 0
	v_addc_co_u32_e64 v171, vcc, v171, v171, s[48:49]
	v_addc_co_u32_e64 v172, vcc, v172, v172, s[50:51]
	v_lshlrev_b32_e32 v171, v167, v171
	v_lshlrev_b32_e32 v172, v167, v172
	s_nop 0
	v_or_b32_dpp v171, v171, v171 quad_perm:[1,0,3,2] row_mask:0xf bank_mask:0xf
	v_or_b32_dpp v172, v172, v172 quad_perm:[1,0,3,2] row_mask:0xf bank_mask:0xf
	s_nop 0
	v_or_b32_dpp v171, v171, v171 quad_perm:[2,3,0,1] row_mask:0xf bank_mask:0xf
	v_or_b32_dpp v172, v172, v172 quad_perm:[2,3,0,1] row_mask:0xf bank_mask:0xf
	s_nop 0
	v_or_b32_dpp v171, v171, v171 row_half_mirror row_mask:0xf bank_mask:0xf
	v_or_b32_dpp v172, v172, v172 row_half_mirror row_mask:0xf bank_mask:0xf
	s_mov_b64 exec, s[80:81]
	global_store_dword v168, v171, s[24:25] offset:960 sc1
	global_store_dword v168, v172, s[24:25] offset:992 sc1
	s_mov_b64 exec, -1
.Ltk0_zf:
	s_lshl_b32 s93, s23, 3
	v_add_u32_e32 v163, s93, v204
	v_cmp_gt_u32_e32 vcc, 0x100, v163
	s_and_saveexec_b64 s[82:83], vcc
	v_lshlrev_b32_e32 v164, 2, v163
	global_store_dword v164, v1, s[24:25] sc1
	s_mov_b64 exec, s[82:83]
	v_add_u32_e32 v163, 64, v163
	v_cmp_gt_u32_e32 vcc, 0x100, v163
	s_and_saveexec_b64 s[82:83], vcc
	v_lshlrev_b32_e32 v164, 2, v163
	global_store_dword v164, v1, s[24:25] sc1
	s_mov_b64 exec, s[82:83]
	v_add_u32_e32 v163, 64, v163
	v_cmp_gt_u32_e32 vcc, 0x100, v163
	s_and_saveexec_b64 s[82:83], vcc
	v_lshlrev_b32_e32 v164, 2, v163
	global_store_dword v164, v1, s[24:25] sc1
	s_mov_b64 exec, s[82:83]
	v_add_u32_e32 v163, 64, v163
	v_cmp_gt_u32_e32 vcc, 0x100, v163
	s_and_saveexec_b64 s[82:83], vcc
	v_lshlrev_b32_e32 v164, 2, v163
	global_store_dword v164, v1, s[24:25] sc1
	s_mov_b64 exec, s[82:83]
	v_add_u32_e32 v163, 64, v163
	s_mov_b32 s38, 0xf800000
	s_mov_b64 s[40:41], 0x44c00100
	s_mov_b64 s[42:43], 0x44c00200
	s_mov_b64 s[44:45], 0x400
	s_movk_i32 s39, 0x1000
	s_branch .LBB0_955

.Ltk1_zf:
	s_lshl_b32 s93, s23, 3
	v_add_u32_e32 v163, s93, v204
	v_cmp_gt_u32_e32 vcc, 0x100, v163
	s_and_saveexec_b64 s[82:83], vcc
	v_lshlrev_b32_e32 v164, 2, v163
	global_store_dword v164, v1, s[24:25] sc1
	s_mov_b64 exec, s[82:83]
	v_add_u32_e32 v163, 64, v163
	v_cmp_gt_u32_e32 vcc, 0x100, v163
	s_and_saveexec_b64 s[82:83], vcc
	v_lshlrev_b32_e32 v164, 2, v163
	global_store_dword v164, v1, s[24:25] sc1
	s_mov_b64 exec, s[82:83]
	v_add_u32_e32 v163, 64, v163
	v_cmp_gt_u32_e32 vcc, 0x100, v163
	s_and_saveexec_b64 s[82:83], vcc
	v_lshlrev_b32_e32 v164, 2, v163
	global_store_dword v164, v1, s[24:25] sc1
	s_mov_b64 exec, s[82:83]
	v_add_u32_e32 v163, 64, v163
	v_cmp_gt_u32_e32 vcc, 0x100, v163
	s_and_saveexec_b64 s[82:83], vcc
	v_lshlrev_b32_e32 v164, 2, v163
	global_store_dword v164, v1, s[24:25] sc1
	s_mov_b64 exec, s[82:83]
	v_add_u32_e32 v163, 64, v163
	s_mov_b64 s[44:45], 0x44c00100
	s_mov_b64 s[46:47], 0x44c00200
	s_mov_b32 s52, 0x62d00000
	s_mov_b64 s[54:55], 0x400
	s_branch .LBB0_2576
